# fp6 table encode moved from the routing phase into the PEER-query GEMM phase (first-dispatched workgroup encodes before its tiles, partner after)
# baseline (speedup 1.0000x reference)
; __global__ void __launch_bounds__(256, 2) fwd_megakernel(Params p) {
;     ...
;   for (int jt = (bid >> 3); jt < 8 * 16; jt += (nb >> 3)) {
;     const int pn = jt >> 3, pm = (bid & 7) * 8 + (jt & 7);
;     const u16* A = p.h + (size_t)pm * 256 * 2048;
;     gemm_tile256([&](int r, int k) { return A + (size_t)r * 2048 + k; }, p.Wt_q + (size_t)pn * 128 * 2048, 2048, 2048,
;     ...
;   if (bid < (nb >> 1)) {
;   for (size_t blk = (size_t)bid * 256 + tid; blk < (size_t)16384 * 64; blk += (size_t)nb * 256) {
; #pragma unroll
;     for (int tb = 0; tb < 2; ++tb) {
;       const float* src = (tb ? p.peer_up : p.peer_down) + blk * 32;
;       const float sc = tb ? UP_SCALE : DOWN_SCALE;
;       v16f va, vb;
; #pragma unroll
;       for (int q = 0; q < 4; ++q) {
;         const float4 x = *(const float4*)(src + q * 8), y = *(const float4*)(src + q * 8 + 4);
;         va[q * 4] = x.x * sc; vb[q * 4] = x.y * sc; va[q * 4 + 1] = x.z * sc; vb[q * 4 + 1] = x.w * sc;
;         va[q * 4 + 2] = y.x * sc; vb[q * 4 + 2] = y.y * sc; va[q * 4 + 3] = y.z * sc; vb[q * 4 + 3] = y.w * sc;
;       }
;       const v6u o = __builtin_amdgcn_cvt_scalef32_2xpk16_fp6_f32(va, vb, 1.0f);
;       unsigned char* dst = (tb ? p.up8 : p.down8) + blk * 24;
;       *(u32x2*)dst = u32x2{o[0], o[1]}; *(u32x2*)(dst + 8) = u32x2{o[2], o[3]}; *(u32x2*)(dst + 16) = u32x2{o[4], o[5]};
;     }
;   }
.LBB0_1365:
	s_or_b64 exec, exec, s[6:7]
	v_mov_b32_e32 v1, v0
	s_andn2_b64 vcc, exec, s[0:1]
	s_waitcnt lgkmcnt(0)
	s_barrier
	s_cbranch_vccnz .LBB0_1384
	s_lshr_b32 s0, s92, 1
	s_cmp_lt_u32 s94, s0
	s_cbranch_scc0 .Lenc_end_a
	v_readlane_b32 s40, v254, 8
	v_readlane_b32 s41, v254, 9
	v_readlane_b32 s42, v254, 10
	v_readlane_b32 s43, v254, 11
	s_nop 4
	s_mov_b64 exec, -1
	v_lshrrev_b32_e32 v54, 6, v0
	v_and_b32_e32 v55, 63, v0
	v_lshlrev_b32_e32 v52, 13, v54
	v_lshl_or_b32 v52, v55, 4, v52
	v_mul_u32_u24_e32 v53, 0xc00, v54
	v_lshl_or_b32 v53, v55, 4, v53
	v_add_u32_e32 v54, 0x1000, v52
	s_lshl_b32 s10, s94, 8
	s_lshl_b32 s11, s92, 8
	s_lshl_b32 s12, s92, 15
	s_mul_i32 s13, s92, 0x3000
	s_mov_b32 s16, 0x42800000
	s_lshl_b32 s0, s94, 15
	s_add_u32 s2, s40, s0
	s_addc_u32 s3, s41, 0
	s_add_u32 s4, s42, s0
	s_addc_u32 s5, s43, 0
	s_mul_i32 s0, s94, 0x3000
	s_add_u32 s6, s62, s0
	s_addc_u32 s7, s63, 0
	s_cmp_lt_u32 s10, 0x100000
	s_cbranch_scc0 .Lenc_end_a
	s_cmpk_lg_u32 s92, 0x200
	s_cbranch_scc1 .Lenc_generic_a
	global_load_dwordx4 v[56:59], v52, s[2:3] sc0 sc1 nt
	global_load_dwordx4 v[60:63], v52, s[2:3] offset:1024 sc0 sc1 nt
	global_load_dwordx4 v[64:67], v52, s[2:3] offset:2048 sc0 sc1 nt
	global_load_dwordx4 v[68:71], v52, s[2:3] offset:3072 sc0 sc1 nt
	global_load_dwordx4 v[72:75], v54, s[2:3] sc0 sc1 nt
	global_load_dwordx4 v[76:79], v54, s[2:3] offset:1024 sc0 sc1 nt
	global_load_dwordx4 v[80:83], v54, s[2:3] offset:2048 sc0 sc1 nt
	global_load_dwordx4 v[84:87], v54, s[2:3] offset:3072 sc0 sc1 nt
	s_waitcnt vmcnt(0)
	v_mul_f32_e32 v2, s16, v56
	v_mul_f32_e32 v3, s16, v58
	v_mul_f32_e32 v4, s16, v60
	v_mul_f32_e32 v5, s16, v62
	v_mul_f32_e32 v6, s16, v64
	v_mul_f32_e32 v7, s16, v66
	v_mul_f32_e32 v8, s16, v68
	v_mul_f32_e32 v9, s16, v70
	v_mul_f32_e32 v10, s16, v72
	v_mul_f32_e32 v11, s16, v74
	v_mul_f32_e32 v12, s16, v76
	v_mul_f32_e32 v13, s16, v78
	v_mul_f32_e32 v14, s16, v80
	v_mul_f32_e32 v15, s16, v82
	v_mul_f32_e32 v16, s16, v84
	v_mul_f32_e32 v17, s16, v86
	v_mul_f32_e32 v18, s16, v57
	v_mul_f32_e32 v19, s16, v59
	v_mul_f32_e32 v20, s16, v61
	v_mul_f32_e32 v21, s16, v63
	v_mul_f32_e32 v22, s16, v65
	v_mul_f32_e32 v23, s16, v67
	v_mul_f32_e32 v24, s16, v69
	v_mul_f32_e32 v25, s16, v71
	v_mul_f32_e32 v26, s16, v73
	v_mul_f32_e32 v27, s16, v75
	v_mul_f32_e32 v28, s16, v77
	v_mul_f32_e32 v29, s16, v79
	v_mul_f32_e32 v30, s16, v81
	v_mul_f32_e32 v31, s16, v83
	v_mul_f32_e32 v32, s16, v85
	v_mul_f32_e32 v33, s16, v87
	s_nop 0
	v_cvt_scalef32_2xpk16_fp6_f32 v[40:45], v[2:17], v[18:33], 1.0
	global_load_dwordx4 v[56:59], v52, s[4:5] sc0 sc1 nt
	global_load_dwordx4 v[60:63], v52, s[4:5] offset:1024 sc0 sc1 nt
	global_load_dwordx4 v[64:67], v52, s[4:5] offset:2048 sc0 sc1 nt
	global_load_dwordx4 v[68:71], v52, s[4:5] offset:3072 sc0 sc1 nt
	global_load_dwordx4 v[72:75], v54, s[4:5] sc0 sc1 nt
	global_load_dwordx4 v[76:79], v54, s[4:5] offset:1024 sc0 sc1 nt
	global_load_dwordx4 v[80:83], v54, s[4:5] offset:2048 sc0 sc1 nt
	global_load_dwordx4 v[84:87], v54, s[4:5] offset:3072 sc0 sc1 nt
	s_add_u32 s2, s2, s12
	s_addc_u32 s3, s3, 0
	s_add_u32 s4, s4, s12
	s_addc_u32 s5, s5, 0
	s_waitcnt vmcnt(0)
	v_mul_f32_e32 v2, 4.0, v56
	v_mul_f32_e32 v3, 4.0, v58
	v_mul_f32_e32 v4, 4.0, v60
	v_mul_f32_e32 v5, 4.0, v62
	v_mul_f32_e32 v6, 4.0, v64
	v_mul_f32_e32 v7, 4.0, v66
	v_mul_f32_e32 v8, 4.0, v68
	v_mul_f32_e32 v9, 4.0, v70
	v_mul_f32_e32 v10, 4.0, v72
	v_mul_f32_e32 v11, 4.0, v74
	v_mul_f32_e32 v12, 4.0, v76
	v_mul_f32_e32 v13, 4.0, v78
	v_mul_f32_e32 v14, 4.0, v80
	v_mul_f32_e32 v15, 4.0, v82
	v_mul_f32_e32 v16, 4.0, v84
	v_mul_f32_e32 v17, 4.0, v86
	v_mul_f32_e32 v18, 4.0, v57
	v_mul_f32_e32 v19, 4.0, v59
	v_mul_f32_e32 v20, 4.0, v61
	v_mul_f32_e32 v21, 4.0, v63
	v_mul_f32_e32 v22, 4.0, v65
	v_mul_f32_e32 v23, 4.0, v67
	v_mul_f32_e32 v24, 4.0, v69
	v_mul_f32_e32 v25, 4.0, v71
	v_mul_f32_e32 v26, 4.0, v73
	v_mul_f32_e32 v27, 4.0, v75
	v_mul_f32_e32 v28, 4.0, v77
	v_mul_f32_e32 v29, 4.0, v79
	v_mul_f32_e32 v30, 4.0, v81
	v_mul_f32_e32 v31, 4.0, v83
	v_mul_f32_e32 v32, 4.0, v85
	v_mul_f32_e32 v33, 4.0, v87
	s_nop 0
	v_cvt_scalef32_2xpk16_fp6_f32 v[46:51], v[2:17], v[18:33], 1.0
	global_store_dwordx4 v53, v[40:43], s[6:7]
	global_store_dwordx4 v53, v[48:51], s[6:7] offset:1024
	global_store_dwordx4 v53, v[44:47], s[6:7] offset:2048
	s_add_u32 s6, s6, s13
	s_addc_u32 s7, s7, 0
	global_load_dwordx4 v[56:59], v52, s[2:3] sc0 sc1 nt
	global_load_dwordx4 v[60:63], v52, s[2:3] offset:1024 sc0 sc1 nt
	global_load_dwordx4 v[64:67], v52, s[2:3] offset:2048 sc0 sc1 nt
	global_load_dwordx4 v[68:71], v52, s[2:3] offset:3072 sc0 sc1 nt
	global_load_dwordx4 v[72:75], v54, s[2:3] sc0 sc1 nt
	global_load_dwordx4 v[76:79], v54, s[2:3] offset:1024 sc0 sc1 nt
	global_load_dwordx4 v[80:83], v54, s[2:3] offset:2048 sc0 sc1 nt
	global_load_dwordx4 v[84:87], v54, s[2:3] offset:3072 sc0 sc1 nt
	s_waitcnt vmcnt(0)
; __global__ void __launch_bounds__(256, 2) fwd_megakernel(Params p) {
;     ...
;   for (size_t blk = (size_t)bid * 256 + tid; blk < (size_t)16384 * 64; blk += (size_t)nb * 256) {
; #pragma unroll
;     for (int tb = 0; tb < 2; ++tb) {
;       const float* src = (tb ? p.peer_up : p.peer_down) + blk * 32;
;       const float sc = tb ? UP_SCALE : DOWN_SCALE;
;       v16f va, vb;
; #pragma unroll
;       for (int q = 0; q < 4; ++q) {
;         const float4 x = *(const float4*)(src + q * 8), y = *(const float4*)(src + q * 8 + 4);
;         va[q * 4] = x.x * sc; vb[q * 4] = x.y * sc; va[q * 4 + 1] = x.z * sc; vb[q * 4 + 1] = x.w * sc;
;         va[q * 4 + 2] = y.x * sc; vb[q * 4 + 2] = y.y * sc; va[q * 4 + 3] = y.z * sc; vb[q * 4 + 3] = y.w * sc;
;       }
;       const v6u o = __builtin_amdgcn_cvt_scalef32_2xpk16_fp6_f32(va, vb, 1.0f);
;       unsigned char* dst = (tb ? p.up8 : p.down8) + blk * 24;
;       *(u32x2*)dst = u32x2{o[0], o[1]}; *(u32x2*)(dst + 8) = u32x2{o[2], o[3]}; *(u32x2*)(dst + 16) = u32x2{o[4], o[5]};
;     }
;   }
	v_mul_f32_e32 v2, s16, v56
	v_mul_f32_e32 v3, s16, v58
	v_mul_f32_e32 v4, s16, v60
	v_mul_f32_e32 v5, s16, v62
	v_mul_f32_e32 v6, s16, v64
	v_mul_f32_e32 v7, s16, v66
	v_mul_f32_e32 v8, s16, v68
	v_mul_f32_e32 v9, s16, v70
	v_mul_f32_e32 v10, s16, v72
	v_mul_f32_e32 v11, s16, v74
	v_mul_f32_e32 v12, s16, v76
	v_mul_f32_e32 v13, s16, v78
	v_mul_f32_e32 v14, s16, v80
	v_mul_f32_e32 v15, s16, v82
	v_mul_f32_e32 v16, s16, v84
	v_mul_f32_e32 v17, s16, v86
	v_mul_f32_e32 v18, s16, v57
	v_mul_f32_e32 v19, s16, v59
	v_mul_f32_e32 v20, s16, v61
	v_mul_f32_e32 v21, s16, v63
	v_mul_f32_e32 v22, s16, v65
	v_mul_f32_e32 v23, s16, v67
	v_mul_f32_e32 v24, s16, v69
	v_mul_f32_e32 v25, s16, v71
	v_mul_f32_e32 v26, s16, v73
	v_mul_f32_e32 v27, s16, v75
	v_mul_f32_e32 v28, s16, v77
	v_mul_f32_e32 v29, s16, v79
	v_mul_f32_e32 v30, s16, v81
	v_mul_f32_e32 v31, s16, v83
	v_mul_f32_e32 v32, s16, v85
	v_mul_f32_e32 v33, s16, v87
	s_nop 0
	v_cvt_scalef32_2xpk16_fp6_f32 v[40:45], v[2:17], v[18:33], 1.0
	global_load_dwordx4 v[56:59], v52, s[4:5] sc0 sc1 nt
	global_load_dwordx4 v[60:63], v52, s[4:5] offset:1024 sc0 sc1 nt
	global_load_dwordx4 v[64:67], v52, s[4:5] offset:2048 sc0 sc1 nt
	global_load_dwordx4 v[68:71], v52, s[4:5] offset:3072 sc0 sc1 nt
	global_load_dwordx4 v[72:75], v54, s[4:5] sc0 sc1 nt
	global_load_dwordx4 v[76:79], v54, s[4:5] offset:1024 sc0 sc1 nt
	global_load_dwordx4 v[80:83], v54, s[4:5] offset:2048 sc0 sc1 nt
	global_load_dwordx4 v[84:87], v54, s[4:5] offset:3072 sc0 sc1 nt
	s_add_u32 s2, s2, s12
	s_addc_u32 s3, s3, 0
	s_add_u32 s4, s4, s12
	s_addc_u32 s5, s5, 0
	s_waitcnt vmcnt(0)
	v_mul_f32_e32 v2, 4.0, v56
	v_mul_f32_e32 v3, 4.0, v58
	v_mul_f32_e32 v4, 4.0, v60
	v_mul_f32_e32 v5, 4.0, v62
	v_mul_f32_e32 v6, 4.0, v64
	v_mul_f32_e32 v7, 4.0, v66
	v_mul_f32_e32 v8, 4.0, v68
	v_mul_f32_e32 v9, 4.0, v70
	v_mul_f32_e32 v10, 4.0, v72
	v_mul_f32_e32 v11, 4.0, v74
	v_mul_f32_e32 v12, 4.0, v76
	v_mul_f32_e32 v13, 4.0, v78
	v_mul_f32_e32 v14, 4.0, v80
	v_mul_f32_e32 v15, 4.0, v82
	v_mul_f32_e32 v16, 4.0, v84
	v_mul_f32_e32 v17, 4.0, v86
	v_mul_f32_e32 v18, 4.0, v57
	v_mul_f32_e32 v19, 4.0, v59
	v_mul_f32_e32 v20, 4.0, v61
	v_mul_f32_e32 v21, 4.0, v63
	v_mul_f32_e32 v22, 4.0, v65
	v_mul_f32_e32 v23, 4.0, v67
	v_mul_f32_e32 v24, 4.0, v69
	v_mul_f32_e32 v25, 4.0, v71
	v_mul_f32_e32 v26, 4.0, v73
	v_mul_f32_e32 v27, 4.0, v75
	v_mul_f32_e32 v28, 4.0, v77
	v_mul_f32_e32 v29, 4.0, v79
	v_mul_f32_e32 v30, 4.0, v81
	v_mul_f32_e32 v31, 4.0, v83
	v_mul_f32_e32 v32, 4.0, v85
	v_mul_f32_e32 v33, 4.0, v87
	s_nop 0
	v_cvt_scalef32_2xpk16_fp6_f32 v[46:51], v[2:17], v[18:33], 1.0
	global_store_dwordx4 v53, v[40:43], s[6:7]
	global_store_dwordx4 v53, v[48:51], s[6:7] offset:1024
	global_store_dwordx4 v53, v[44:47], s[6:7] offset:2048
	s_add_u32 s6, s6, s13
	s_addc_u32 s7, s7, 0
	global_load_dwordx4 v[56:59], v52, s[2:3] sc0 sc1 nt
	global_load_dwordx4 v[60:63], v52, s[2:3] offset:1024 sc0 sc1 nt
	global_load_dwordx4 v[64:67], v52, s[2:3] offset:2048 sc0 sc1 nt
	global_load_dwordx4 v[68:71], v52, s[2:3] offset:3072 sc0 sc1 nt
	global_load_dwordx4 v[72:75], v54, s[2:3] sc0 sc1 nt
	global_load_dwordx4 v[76:79], v54, s[2:3] offset:1024 sc0 sc1 nt
	global_load_dwordx4 v[80:83], v54, s[2:3] offset:2048 sc0 sc1 nt
	global_load_dwordx4 v[84:87], v54, s[2:3] offset:3072 sc0 sc1 nt
	s_waitcnt vmcnt(0)
	v_mul_f32_e32 v2, s16, v56
	v_mul_f32_e32 v3, s16, v58
	v_mul_f32_e32 v4, s16, v60
	v_mul_f32_e32 v5, s16, v62
	v_mul_f32_e32 v6, s16, v64
	v_mul_f32_e32 v7, s16, v66
	v_mul_f32_e32 v8, s16, v68
	v_mul_f32_e32 v9, s16, v70
	v_mul_f32_e32 v10, s16, v72
	v_mul_f32_e32 v11, s16, v74
	v_mul_f32_e32 v12, s16, v76
	v_mul_f32_e32 v13, s16, v78
	v_mul_f32_e32 v14, s16, v80
	v_mul_f32_e32 v15, s16, v82
	v_mul_f32_e32 v16, s16, v84
	v_mul_f32_e32 v17, s16, v86
	v_mul_f32_e32 v18, s16, v57
	v_mul_f32_e32 v19, s16, v59
	v_mul_f32_e32 v20, s16, v61
	v_mul_f32_e32 v21, s16, v63
	v_mul_f32_e32 v22, s16, v65
	v_mul_f32_e32 v23, s16, v67
	v_mul_f32_e32 v24, s16, v69
	v_mul_f32_e32 v25, s16, v71
	v_mul_f32_e32 v26, s16, v73
	v_mul_f32_e32 v27, s16, v75
	v_mul_f32_e32 v28, s16, v77
	v_mul_f32_e32 v29, s16, v79
	v_mul_f32_e32 v30, s16, v81
	v_mul_f32_e32 v31, s16, v83
	v_mul_f32_e32 v32, s16, v85
	v_mul_f32_e32 v33, s16, v87
	s_nop 0
	v_cvt_scalef32_2xpk16_fp6_f32 v[40:45], v[2:17], v[18:33], 1.0
	global_load_dwordx4 v[56:59], v52, s[4:5] sc0 sc1 nt
	global_load_dwordx4 v[60:63], v52, s[4:5] offset:1024 sc0 sc1 nt
	global_load_dwordx4 v[64:67], v52, s[4:5] offset:2048 sc0 sc1 nt
	global_load_dwordx4 v[68:71], v52, s[4:5] offset:3072 sc0 sc1 nt
	global_load_dwordx4 v[72:75], v54, s[4:5] sc0 sc1 nt
	global_load_dwordx4 v[76:79], v54, s[4:5] offset:1024 sc0 sc1 nt
	global_load_dwordx4 v[80:83], v54, s[4:5] offset:2048 sc0 sc1 nt
	global_load_dwordx4 v[84:87], v54, s[4:5] offset:3072 sc0 sc1 nt
	s_add_u32 s2, s2, s12
	s_addc_u32 s3, s3, 0
	s_add_u32 s4, s4, s12
	s_addc_u32 s5, s5, 0
	s_waitcnt vmcnt(0)
; __global__ void __launch_bounds__(256, 2) fwd_megakernel(Params p) {
;     ...
;   for (size_t blk = (size_t)bid * 256 + tid; blk < (size_t)16384 * 64; blk += (size_t)nb * 256) {
; #pragma unroll
;     for (int tb = 0; tb < 2; ++tb) {
;       const float* src = (tb ? p.peer_up : p.peer_down) + blk * 32;
;       const float sc = tb ? UP_SCALE : DOWN_SCALE;
;       v16f va, vb;
; #pragma unroll
;       for (int q = 0; q < 4; ++q) {
;         const float4 x = *(const float4*)(src + q * 8), y = *(const float4*)(src + q * 8 + 4);
;         va[q * 4] = x.x * sc; vb[q * 4] = x.y * sc; va[q * 4 + 1] = x.z * sc; vb[q * 4 + 1] = x.w * sc;
;         va[q * 4 + 2] = y.x * sc; vb[q * 4 + 2] = y.y * sc; va[q * 4 + 3] = y.z * sc; vb[q * 4 + 3] = y.w * sc;
;       }
;       const v6u o = __builtin_amdgcn_cvt_scalef32_2xpk16_fp6_f32(va, vb, 1.0f);
;       unsigned char* dst = (tb ? p.up8 : p.down8) + blk * 24;
;       *(u32x2*)dst = u32x2{o[0], o[1]}; *(u32x2*)(dst + 8) = u32x2{o[2], o[3]}; *(u32x2*)(dst + 16) = u32x2{o[4], o[5]};
;     }
;   }
	v_mul_f32_e32 v2, 4.0, v56
	v_mul_f32_e32 v3, 4.0, v58
	v_mul_f32_e32 v4, 4.0, v60
	v_mul_f32_e32 v5, 4.0, v62
	v_mul_f32_e32 v6, 4.0, v64
	v_mul_f32_e32 v7, 4.0, v66
	v_mul_f32_e32 v8, 4.0, v68
	v_mul_f32_e32 v9, 4.0, v70
	v_mul_f32_e32 v10, 4.0, v72
	v_mul_f32_e32 v11, 4.0, v74
	v_mul_f32_e32 v12, 4.0, v76
	v_mul_f32_e32 v13, 4.0, v78
	v_mul_f32_e32 v14, 4.0, v80
	v_mul_f32_e32 v15, 4.0, v82
	v_mul_f32_e32 v16, 4.0, v84
	v_mul_f32_e32 v17, 4.0, v86
	v_mul_f32_e32 v18, 4.0, v57
	v_mul_f32_e32 v19, 4.0, v59
	v_mul_f32_e32 v20, 4.0, v61
	v_mul_f32_e32 v21, 4.0, v63
	v_mul_f32_e32 v22, 4.0, v65
	v_mul_f32_e32 v23, 4.0, v67
	v_mul_f32_e32 v24, 4.0, v69
	v_mul_f32_e32 v25, 4.0, v71
	v_mul_f32_e32 v26, 4.0, v73
	v_mul_f32_e32 v27, 4.0, v75
	v_mul_f32_e32 v28, 4.0, v77
	v_mul_f32_e32 v29, 4.0, v79
	v_mul_f32_e32 v30, 4.0, v81
	v_mul_f32_e32 v31, 4.0, v83
	v_mul_f32_e32 v32, 4.0, v85
	v_mul_f32_e32 v33, 4.0, v87
	s_nop 0
	v_cvt_scalef32_2xpk16_fp6_f32 v[46:51], v[2:17], v[18:33], 1.0
	global_store_dwordx4 v53, v[40:43], s[6:7]
	global_store_dwordx4 v53, v[48:51], s[6:7] offset:1024
	global_store_dwordx4 v53, v[44:47], s[6:7] offset:2048
	s_add_u32 s6, s6, s13
	s_addc_u32 s7, s7, 0
	global_load_dwordx4 v[56:59], v52, s[2:3] sc0 sc1 nt
	global_load_dwordx4 v[60:63], v52, s[2:3] offset:1024 sc0 sc1 nt
	global_load_dwordx4 v[64:67], v52, s[2:3] offset:2048 sc0 sc1 nt
	global_load_dwordx4 v[68:71], v52, s[2:3] offset:3072 sc0 sc1 nt
	global_load_dwordx4 v[72:75], v54, s[2:3] sc0 sc1 nt
	global_load_dwordx4 v[76:79], v54, s[2:3] offset:1024 sc0 sc1 nt
	global_load_dwordx4 v[80:83], v54, s[2:3] offset:2048 sc0 sc1 nt
	global_load_dwordx4 v[84:87], v54, s[2:3] offset:3072 sc0 sc1 nt
	s_waitcnt vmcnt(0)
	v_mul_f32_e32 v2, s16, v56
	v_mul_f32_e32 v3, s16, v58
	v_mul_f32_e32 v4, s16, v60
	v_mul_f32_e32 v5, s16, v62
	v_mul_f32_e32 v6, s16, v64
	v_mul_f32_e32 v7, s16, v66
	v_mul_f32_e32 v8, s16, v68
	v_mul_f32_e32 v9, s16, v70
	v_mul_f32_e32 v10, s16, v72
	v_mul_f32_e32 v11, s16, v74
	v_mul_f32_e32 v12, s16, v76
	v_mul_f32_e32 v13, s16, v78
	v_mul_f32_e32 v14, s16, v80
	v_mul_f32_e32 v15, s16, v82
	v_mul_f32_e32 v16, s16, v84
	v_mul_f32_e32 v17, s16, v86
	v_mul_f32_e32 v18, s16, v57
	v_mul_f32_e32 v19, s16, v59
	v_mul_f32_e32 v20, s16, v61
	v_mul_f32_e32 v21, s16, v63
	v_mul_f32_e32 v22, s16, v65
	v_mul_f32_e32 v23, s16, v67
	v_mul_f32_e32 v24, s16, v69
	v_mul_f32_e32 v25, s16, v71
	v_mul_f32_e32 v26, s16, v73
	v_mul_f32_e32 v27, s16, v75
	v_mul_f32_e32 v28, s16, v77
	v_mul_f32_e32 v29, s16, v79
	v_mul_f32_e32 v30, s16, v81
	v_mul_f32_e32 v31, s16, v83
	v_mul_f32_e32 v32, s16, v85
	v_mul_f32_e32 v33, s16, v87
	s_nop 0
	v_cvt_scalef32_2xpk16_fp6_f32 v[40:45], v[2:17], v[18:33], 1.0
	global_load_dwordx4 v[56:59], v52, s[4:5] sc0 sc1 nt
	global_load_dwordx4 v[60:63], v52, s[4:5] offset:1024 sc0 sc1 nt
	global_load_dwordx4 v[64:67], v52, s[4:5] offset:2048 sc0 sc1 nt
	global_load_dwordx4 v[68:71], v52, s[4:5] offset:3072 sc0 sc1 nt
	global_load_dwordx4 v[72:75], v54, s[4:5] sc0 sc1 nt
	global_load_dwordx4 v[76:79], v54, s[4:5] offset:1024 sc0 sc1 nt
	global_load_dwordx4 v[80:83], v54, s[4:5] offset:2048 sc0 sc1 nt
	global_load_dwordx4 v[84:87], v54, s[4:5] offset:3072 sc0 sc1 nt
	s_add_u32 s2, s2, s12
	s_addc_u32 s3, s3, 0
	s_add_u32 s4, s4, s12
	s_addc_u32 s5, s5, 0
	s_waitcnt vmcnt(0)
	v_mul_f32_e32 v2, 4.0, v56
	v_mul_f32_e32 v3, 4.0, v58
	v_mul_f32_e32 v4, 4.0, v60
	v_mul_f32_e32 v5, 4.0, v62
	v_mul_f32_e32 v6, 4.0, v64
	v_mul_f32_e32 v7, 4.0, v66
	v_mul_f32_e32 v8, 4.0, v68
	v_mul_f32_e32 v9, 4.0, v70
	v_mul_f32_e32 v10, 4.0, v72
	v_mul_f32_e32 v11, 4.0, v74
	v_mul_f32_e32 v12, 4.0, v76
	v_mul_f32_e32 v13, 4.0, v78
	v_mul_f32_e32 v14, 4.0, v80
	v_mul_f32_e32 v15, 4.0, v82
	v_mul_f32_e32 v16, 4.0, v84
	v_mul_f32_e32 v17, 4.0, v86
	v_mul_f32_e32 v18, 4.0, v57
	v_mul_f32_e32 v19, 4.0, v59
	v_mul_f32_e32 v20, 4.0, v61
	v_mul_f32_e32 v21, 4.0, v63
	v_mul_f32_e32 v22, 4.0, v65
	v_mul_f32_e32 v23, 4.0, v67
	v_mul_f32_e32 v24, 4.0, v69
	v_mul_f32_e32 v25, 4.0, v71
	v_mul_f32_e32 v26, 4.0, v73
	v_mul_f32_e32 v27, 4.0, v75
	v_mul_f32_e32 v28, 4.0, v77
	v_mul_f32_e32 v29, 4.0, v79
	v_mul_f32_e32 v30, 4.0, v81
	v_mul_f32_e32 v31, 4.0, v83
	v_mul_f32_e32 v32, 4.0, v85
	v_mul_f32_e32 v33, 4.0, v87
	s_nop 0
	v_cvt_scalef32_2xpk16_fp6_f32 v[46:51], v[2:17], v[18:33], 1.0
	global_store_dwordx4 v53, v[40:43], s[6:7]
	global_store_dwordx4 v53, v[48:51], s[6:7] offset:1024
	global_store_dwordx4 v53, v[44:47], s[6:7] offset:2048
	s_add_u32 s6, s6, s13
	s_addc_u32 s7, s7, 0
	global_load_dwordx4 v[56:59], v52, s[2:3] sc0 sc1 nt
	global_load_dwordx4 v[60:63], v52, s[2:3] offset:1024 sc0 sc1 nt
	global_load_dwordx4 v[64:67], v52, s[2:3] offset:2048 sc0 sc1 nt
	global_load_dwordx4 v[68:71], v52, s[2:3] offset:3072 sc0 sc1 nt
	global_load_dwordx4 v[72:75], v54, s[2:3] sc0 sc1 nt
	global_load_dwordx4 v[76:79], v54, s[2:3] offset:1024 sc0 sc1 nt
	global_load_dwordx4 v[80:83], v54, s[2:3] offset:2048 sc0 sc1 nt
	global_load_dwordx4 v[84:87], v54, s[2:3] offset:3072 sc0 sc1 nt
	s_waitcnt vmcnt(0)
; __global__ void __launch_bounds__(256, 2) fwd_megakernel(Params p) {
;     ...
;   for (size_t blk = (size_t)bid * 256 + tid; blk < (size_t)16384 * 64; blk += (size_t)nb * 256) {
; #pragma unroll
;     for (int tb = 0; tb < 2; ++tb) {
;       const float* src = (tb ? p.peer_up : p.peer_down) + blk * 32;
;       const float sc = tb ? UP_SCALE : DOWN_SCALE;
;       v16f va, vb;
; #pragma unroll
;       for (int q = 0; q < 4; ++q) {
;         const float4 x = *(const float4*)(src + q * 8), y = *(const float4*)(src + q * 8 + 4);
;         va[q * 4] = x.x * sc; vb[q * 4] = x.y * sc; va[q * 4 + 1] = x.z * sc; vb[q * 4 + 1] = x.w * sc;
;         va[q * 4 + 2] = y.x * sc; vb[q * 4 + 2] = y.y * sc; va[q * 4 + 3] = y.z * sc; vb[q * 4 + 3] = y.w * sc;
;       }
;       const v6u o = __builtin_amdgcn_cvt_scalef32_2xpk16_fp6_f32(va, vb, 1.0f);
;       unsigned char* dst = (tb ? p.up8 : p.down8) + blk * 24;
;       *(u32x2*)dst = u32x2{o[0], o[1]}; *(u32x2*)(dst + 8) = u32x2{o[2], o[3]}; *(u32x2*)(dst + 16) = u32x2{o[4], o[5]};
;     }
;   }
	v_mul_f32_e32 v2, s16, v56
	v_mul_f32_e32 v3, s16, v58
	v_mul_f32_e32 v4, s16, v60
	v_mul_f32_e32 v5, s16, v62
	v_mul_f32_e32 v6, s16, v64
	v_mul_f32_e32 v7, s16, v66
	v_mul_f32_e32 v8, s16, v68
	v_mul_f32_e32 v9, s16, v70
	v_mul_f32_e32 v10, s16, v72
	v_mul_f32_e32 v11, s16, v74
	v_mul_f32_e32 v12, s16, v76
	v_mul_f32_e32 v13, s16, v78
	v_mul_f32_e32 v14, s16, v80
	v_mul_f32_e32 v15, s16, v82
	v_mul_f32_e32 v16, s16, v84
	v_mul_f32_e32 v17, s16, v86
	v_mul_f32_e32 v18, s16, v57
	v_mul_f32_e32 v19, s16, v59
	v_mul_f32_e32 v20, s16, v61
	v_mul_f32_e32 v21, s16, v63
	v_mul_f32_e32 v22, s16, v65
	v_mul_f32_e32 v23, s16, v67
	v_mul_f32_e32 v24, s16, v69
	v_mul_f32_e32 v25, s16, v71
	v_mul_f32_e32 v26, s16, v73
	v_mul_f32_e32 v27, s16, v75
	v_mul_f32_e32 v28, s16, v77
	v_mul_f32_e32 v29, s16, v79
	v_mul_f32_e32 v30, s16, v81
	v_mul_f32_e32 v31, s16, v83
	v_mul_f32_e32 v32, s16, v85
	v_mul_f32_e32 v33, s16, v87
	s_nop 0
	v_cvt_scalef32_2xpk16_fp6_f32 v[40:45], v[2:17], v[18:33], 1.0
	global_load_dwordx4 v[56:59], v52, s[4:5] sc0 sc1 nt
	global_load_dwordx4 v[60:63], v52, s[4:5] offset:1024 sc0 sc1 nt
	global_load_dwordx4 v[64:67], v52, s[4:5] offset:2048 sc0 sc1 nt
	global_load_dwordx4 v[68:71], v52, s[4:5] offset:3072 sc0 sc1 nt
	global_load_dwordx4 v[72:75], v54, s[4:5] sc0 sc1 nt
	global_load_dwordx4 v[76:79], v54, s[4:5] offset:1024 sc0 sc1 nt
	global_load_dwordx4 v[80:83], v54, s[4:5] offset:2048 sc0 sc1 nt
	global_load_dwordx4 v[84:87], v54, s[4:5] offset:3072 sc0 sc1 nt
	s_add_u32 s2, s2, s12
	s_addc_u32 s3, s3, 0
	s_add_u32 s4, s4, s12
	s_addc_u32 s5, s5, 0
	s_waitcnt vmcnt(0)
	v_mul_f32_e32 v2, 4.0, v56
	v_mul_f32_e32 v3, 4.0, v58
	v_mul_f32_e32 v4, 4.0, v60
	v_mul_f32_e32 v5, 4.0, v62
	v_mul_f32_e32 v6, 4.0, v64
	v_mul_f32_e32 v7, 4.0, v66
	v_mul_f32_e32 v8, 4.0, v68
	v_mul_f32_e32 v9, 4.0, v70
	v_mul_f32_e32 v10, 4.0, v72
	v_mul_f32_e32 v11, 4.0, v74
	v_mul_f32_e32 v12, 4.0, v76
	v_mul_f32_e32 v13, 4.0, v78
	v_mul_f32_e32 v14, 4.0, v80
	v_mul_f32_e32 v15, 4.0, v82
	v_mul_f32_e32 v16, 4.0, v84
	v_mul_f32_e32 v17, 4.0, v86
	v_mul_f32_e32 v18, 4.0, v57
	v_mul_f32_e32 v19, 4.0, v59
	v_mul_f32_e32 v20, 4.0, v61
	v_mul_f32_e32 v21, 4.0, v63
	v_mul_f32_e32 v22, 4.0, v65
	v_mul_f32_e32 v23, 4.0, v67
	v_mul_f32_e32 v24, 4.0, v69
	v_mul_f32_e32 v25, 4.0, v71
	v_mul_f32_e32 v26, 4.0, v73
	v_mul_f32_e32 v27, 4.0, v75
	v_mul_f32_e32 v28, 4.0, v77
	v_mul_f32_e32 v29, 4.0, v79
	v_mul_f32_e32 v30, 4.0, v81
	v_mul_f32_e32 v31, 4.0, v83
	v_mul_f32_e32 v32, 4.0, v85
	v_mul_f32_e32 v33, 4.0, v87
	s_nop 0
	v_cvt_scalef32_2xpk16_fp6_f32 v[46:51], v[2:17], v[18:33], 1.0
	global_store_dwordx4 v53, v[40:43], s[6:7]
	global_store_dwordx4 v53, v[48:51], s[6:7] offset:1024
	global_store_dwordx4 v53, v[44:47], s[6:7] offset:2048
	s_add_u32 s6, s6, s13
	s_addc_u32 s7, s7, 0
	global_load_dwordx4 v[56:59], v52, s[2:3] sc0 sc1 nt
	global_load_dwordx4 v[60:63], v52, s[2:3] offset:1024 sc0 sc1 nt
	global_load_dwordx4 v[64:67], v52, s[2:3] offset:2048 sc0 sc1 nt
	global_load_dwordx4 v[68:71], v52, s[2:3] offset:3072 sc0 sc1 nt
	global_load_dwordx4 v[72:75], v54, s[2:3] sc0 sc1 nt
	global_load_dwordx4 v[76:79], v54, s[2:3] offset:1024 sc0 sc1 nt
	global_load_dwordx4 v[80:83], v54, s[2:3] offset:2048 sc0 sc1 nt
	global_load_dwordx4 v[84:87], v54, s[2:3] offset:3072 sc0 sc1 nt
	s_waitcnt vmcnt(0)
	v_mul_f32_e32 v2, s16, v56
	v_mul_f32_e32 v3, s16, v58
	v_mul_f32_e32 v4, s16, v60
	v_mul_f32_e32 v5, s16, v62
	v_mul_f32_e32 v6, s16, v64
	v_mul_f32_e32 v7, s16, v66
	v_mul_f32_e32 v8, s16, v68
	v_mul_f32_e32 v9, s16, v70
	v_mul_f32_e32 v10, s16, v72
	v_mul_f32_e32 v11, s16, v74
	v_mul_f32_e32 v12, s16, v76
	v_mul_f32_e32 v13, s16, v78
	v_mul_f32_e32 v14, s16, v80
	v_mul_f32_e32 v15, s16, v82
	v_mul_f32_e32 v16, s16, v84
	v_mul_f32_e32 v17, s16, v86
	v_mul_f32_e32 v18, s16, v57
	v_mul_f32_e32 v19, s16, v59
	v_mul_f32_e32 v20, s16, v61
	v_mul_f32_e32 v21, s16, v63
	v_mul_f32_e32 v22, s16, v65
	v_mul_f32_e32 v23, s16, v67
	v_mul_f32_e32 v24, s16, v69
	v_mul_f32_e32 v25, s16, v71
	v_mul_f32_e32 v26, s16, v73
	v_mul_f32_e32 v27, s16, v75
	v_mul_f32_e32 v28, s16, v77
	v_mul_f32_e32 v29, s16, v79
	v_mul_f32_e32 v30, s16, v81
	v_mul_f32_e32 v31, s16, v83
	v_mul_f32_e32 v32, s16, v85
	v_mul_f32_e32 v33, s16, v87
	s_nop 0
	v_cvt_scalef32_2xpk16_fp6_f32 v[40:45], v[2:17], v[18:33], 1.0
	global_load_dwordx4 v[56:59], v52, s[4:5] sc0 sc1 nt
	global_load_dwordx4 v[60:63], v52, s[4:5] offset:1024 sc0 sc1 nt
	global_load_dwordx4 v[64:67], v52, s[4:5] offset:2048 sc0 sc1 nt
	global_load_dwordx4 v[68:71], v52, s[4:5] offset:3072 sc0 sc1 nt
	global_load_dwordx4 v[72:75], v54, s[4:5] sc0 sc1 nt
	global_load_dwordx4 v[76:79], v54, s[4:5] offset:1024 sc0 sc1 nt
	global_load_dwordx4 v[80:83], v54, s[4:5] offset:2048 sc0 sc1 nt
	global_load_dwordx4 v[84:87], v54, s[4:5] offset:3072 sc0 sc1 nt
	s_add_u32 s2, s2, s12
	s_addc_u32 s3, s3, 0
	s_add_u32 s4, s4, s12
	s_addc_u32 s5, s5, 0
	s_waitcnt vmcnt(0)
; __global__ void __launch_bounds__(256, 2) fwd_megakernel(Params p) {
;     ...
;   for (size_t blk = (size_t)bid * 256 + tid; blk < (size_t)16384 * 64; blk += (size_t)nb * 256) {
; #pragma unroll
;     for (int tb = 0; tb < 2; ++tb) {
;       const float* src = (tb ? p.peer_up : p.peer_down) + blk * 32;
;       const float sc = tb ? UP_SCALE : DOWN_SCALE;
;       v16f va, vb;
; #pragma unroll
;       for (int q = 0; q < 4; ++q) {
;         const float4 x = *(const float4*)(src + q * 8), y = *(const float4*)(src + q * 8 + 4);
;         va[q * 4] = x.x * sc; vb[q * 4] = x.y * sc; va[q * 4 + 1] = x.z * sc; vb[q * 4 + 1] = x.w * sc;
;         va[q * 4 + 2] = y.x * sc; vb[q * 4 + 2] = y.y * sc; va[q * 4 + 3] = y.z * sc; vb[q * 4 + 3] = y.w * sc;
;       }
;       const v6u o = __builtin_amdgcn_cvt_scalef32_2xpk16_fp6_f32(va, vb, 1.0f);
;       unsigned char* dst = (tb ? p.up8 : p.down8) + blk * 24;
;       *(u32x2*)dst = u32x2{o[0], o[1]}; *(u32x2*)(dst + 8) = u32x2{o[2], o[3]}; *(u32x2*)(dst + 16) = u32x2{o[4], o[5]};
;     }
;   }
	v_mul_f32_e32 v2, 4.0, v56
	v_mul_f32_e32 v3, 4.0, v58
	v_mul_f32_e32 v4, 4.0, v60
	v_mul_f32_e32 v5, 4.0, v62
	v_mul_f32_e32 v6, 4.0, v64
	v_mul_f32_e32 v7, 4.0, v66
	v_mul_f32_e32 v8, 4.0, v68
	v_mul_f32_e32 v9, 4.0, v70
	v_mul_f32_e32 v10, 4.0, v72
	v_mul_f32_e32 v11, 4.0, v74
	v_mul_f32_e32 v12, 4.0, v76
	v_mul_f32_e32 v13, 4.0, v78
	v_mul_f32_e32 v14, 4.0, v80
	v_mul_f32_e32 v15, 4.0, v82
	v_mul_f32_e32 v16, 4.0, v84
	v_mul_f32_e32 v17, 4.0, v86
	v_mul_f32_e32 v18, 4.0, v57
	v_mul_f32_e32 v19, 4.0, v59
	v_mul_f32_e32 v20, 4.0, v61
	v_mul_f32_e32 v21, 4.0, v63
	v_mul_f32_e32 v22, 4.0, v65
	v_mul_f32_e32 v23, 4.0, v67
	v_mul_f32_e32 v24, 4.0, v69
	v_mul_f32_e32 v25, 4.0, v71
	v_mul_f32_e32 v26, 4.0, v73
	v_mul_f32_e32 v27, 4.0, v75
	v_mul_f32_e32 v28, 4.0, v77
	v_mul_f32_e32 v29, 4.0, v79
	v_mul_f32_e32 v30, 4.0, v81
	v_mul_f32_e32 v31, 4.0, v83
	v_mul_f32_e32 v32, 4.0, v85
	v_mul_f32_e32 v33, 4.0, v87
	s_nop 0
	v_cvt_scalef32_2xpk16_fp6_f32 v[46:51], v[2:17], v[18:33], 1.0
	global_store_dwordx4 v53, v[40:43], s[6:7]
	global_store_dwordx4 v53, v[48:51], s[6:7] offset:1024
	global_store_dwordx4 v53, v[44:47], s[6:7] offset:2048
	s_add_u32 s6, s6, s13
	s_addc_u32 s7, s7, 0
	global_load_dwordx4 v[56:59], v52, s[2:3] sc0 sc1 nt
	global_load_dwordx4 v[60:63], v52, s[2:3] offset:1024 sc0 sc1 nt
	global_load_dwordx4 v[64:67], v52, s[2:3] offset:2048 sc0 sc1 nt
	global_load_dwordx4 v[68:71], v52, s[2:3] offset:3072 sc0 sc1 nt
	global_load_dwordx4 v[72:75], v54, s[2:3] sc0 sc1 nt
	global_load_dwordx4 v[76:79], v54, s[2:3] offset:1024 sc0 sc1 nt
	global_load_dwordx4 v[80:83], v54, s[2:3] offset:2048 sc0 sc1 nt
	global_load_dwordx4 v[84:87], v54, s[2:3] offset:3072 sc0 sc1 nt
	s_waitcnt vmcnt(0)
	v_mul_f32_e32 v2, s16, v56
	v_mul_f32_e32 v3, s16, v58
	v_mul_f32_e32 v4, s16, v60
	v_mul_f32_e32 v5, s16, v62
	v_mul_f32_e32 v6, s16, v64
	v_mul_f32_e32 v7, s16, v66
	v_mul_f32_e32 v8, s16, v68
	v_mul_f32_e32 v9, s16, v70
	v_mul_f32_e32 v10, s16, v72
	v_mul_f32_e32 v11, s16, v74
	v_mul_f32_e32 v12, s16, v76
	v_mul_f32_e32 v13, s16, v78
	v_mul_f32_e32 v14, s16, v80
	v_mul_f32_e32 v15, s16, v82
	v_mul_f32_e32 v16, s16, v84
	v_mul_f32_e32 v17, s16, v86
	v_mul_f32_e32 v18, s16, v57
	v_mul_f32_e32 v19, s16, v59
	v_mul_f32_e32 v20, s16, v61
	v_mul_f32_e32 v21, s16, v63
	v_mul_f32_e32 v22, s16, v65
	v_mul_f32_e32 v23, s16, v67
	v_mul_f32_e32 v24, s16, v69
	v_mul_f32_e32 v25, s16, v71
	v_mul_f32_e32 v26, s16, v73
	v_mul_f32_e32 v27, s16, v75
	v_mul_f32_e32 v28, s16, v77
	v_mul_f32_e32 v29, s16, v79
	v_mul_f32_e32 v30, s16, v81
	v_mul_f32_e32 v31, s16, v83
	v_mul_f32_e32 v32, s16, v85
	v_mul_f32_e32 v33, s16, v87
	s_nop 0
	v_cvt_scalef32_2xpk16_fp6_f32 v[40:45], v[2:17], v[18:33], 1.0
	global_load_dwordx4 v[56:59], v52, s[4:5] sc0 sc1 nt
	global_load_dwordx4 v[60:63], v52, s[4:5] offset:1024 sc0 sc1 nt
	global_load_dwordx4 v[64:67], v52, s[4:5] offset:2048 sc0 sc1 nt
	global_load_dwordx4 v[68:71], v52, s[4:5] offset:3072 sc0 sc1 nt
	global_load_dwordx4 v[72:75], v54, s[4:5] sc0 sc1 nt
	global_load_dwordx4 v[76:79], v54, s[4:5] offset:1024 sc0 sc1 nt
	global_load_dwordx4 v[80:83], v54, s[4:5] offset:2048 sc0 sc1 nt
	global_load_dwordx4 v[84:87], v54, s[4:5] offset:3072 sc0 sc1 nt
	s_add_u32 s2, s2, s12
	s_addc_u32 s3, s3, 0
	s_add_u32 s4, s4, s12
	s_addc_u32 s5, s5, 0
	s_waitcnt vmcnt(0)
; __global__ void __launch_bounds__(256, 2) fwd_megakernel(Params p) {
;     ...
;   for (size_t blk = (size_t)bid * 256 + tid; blk < (size_t)16384 * 64; blk += (size_t)nb * 256) {
; #pragma unroll
;     for (int tb = 0; tb < 2; ++tb) {
;       const float* src = (tb ? p.peer_up : p.peer_down) + blk * 32;
;       const float sc = tb ? UP_SCALE : DOWN_SCALE;
;       v16f va, vb;
; #pragma unroll
;       for (int q = 0; q < 4; ++q) {
;         const float4 x = *(const float4*)(src + q * 8), y = *(const float4*)(src + q * 8 + 4);
;         va[q * 4] = x.x * sc; vb[q * 4] = x.y * sc; va[q * 4 + 1] = x.z * sc; vb[q * 4 + 1] = x.w * sc;
;         va[q * 4 + 2] = y.x * sc; vb[q * 4 + 2] = y.y * sc; va[q * 4 + 3] = y.z * sc; vb[q * 4 + 3] = y.w * sc;
;       }
;       const v6u o = __builtin_amdgcn_cvt_scalef32_2xpk16_fp6_f32(va, vb, 1.0f);
;       unsigned char* dst = (tb ? p.up8 : p.down8) + blk * 24;
;       *(u32x2*)dst = u32x2{o[0], o[1]}; *(u32x2*)(dst + 8) = u32x2{o[2], o[3]}; *(u32x2*)(dst + 16) = u32x2{o[4], o[5]};
;     }
;   }
	v_mul_f32_e32 v2, 4.0, v56
	v_mul_f32_e32 v3, 4.0, v58
	v_mul_f32_e32 v4, 4.0, v60
	v_mul_f32_e32 v5, 4.0, v62
	v_mul_f32_e32 v6, 4.0, v64
	v_mul_f32_e32 v7, 4.0, v66
	v_mul_f32_e32 v8, 4.0, v68
	v_mul_f32_e32 v9, 4.0, v70
	v_mul_f32_e32 v10, 4.0, v72
	v_mul_f32_e32 v11, 4.0, v74
	v_mul_f32_e32 v12, 4.0, v76
	v_mul_f32_e32 v13, 4.0, v78
	v_mul_f32_e32 v14, 4.0, v80
	v_mul_f32_e32 v15, 4.0, v82
	v_mul_f32_e32 v16, 4.0, v84
	v_mul_f32_e32 v17, 4.0, v86
	v_mul_f32_e32 v18, 4.0, v57
	v_mul_f32_e32 v19, 4.0, v59
	v_mul_f32_e32 v20, 4.0, v61
	v_mul_f32_e32 v21, 4.0, v63
	v_mul_f32_e32 v22, 4.0, v65
	v_mul_f32_e32 v23, 4.0, v67
	v_mul_f32_e32 v24, 4.0, v69
	v_mul_f32_e32 v25, 4.0, v71
	v_mul_f32_e32 v26, 4.0, v73
	v_mul_f32_e32 v27, 4.0, v75
	v_mul_f32_e32 v28, 4.0, v77
	v_mul_f32_e32 v29, 4.0, v79
	v_mul_f32_e32 v30, 4.0, v81
	v_mul_f32_e32 v31, 4.0, v83
	v_mul_f32_e32 v32, 4.0, v85
	v_mul_f32_e32 v33, 4.0, v87
	s_nop 0
	v_cvt_scalef32_2xpk16_fp6_f32 v[46:51], v[2:17], v[18:33], 1.0
	global_store_dwordx4 v53, v[40:43], s[6:7]
	global_store_dwordx4 v53, v[48:51], s[6:7] offset:1024
	global_store_dwordx4 v53, v[44:47], s[6:7] offset:2048
	s_add_u32 s6, s6, s13
	s_addc_u32 s7, s7, 0
	global_load_dwordx4 v[56:59], v52, s[2:3] sc0 sc1 nt
	global_load_dwordx4 v[60:63], v52, s[2:3] offset:1024 sc0 sc1 nt
	global_load_dwordx4 v[64:67], v52, s[2:3] offset:2048 sc0 sc1 nt
	global_load_dwordx4 v[68:71], v52, s[2:3] offset:3072 sc0 sc1 nt
	global_load_dwordx4 v[72:75], v54, s[2:3] sc0 sc1 nt
	global_load_dwordx4 v[76:79], v54, s[2:3] offset:1024 sc0 sc1 nt
	global_load_dwordx4 v[80:83], v54, s[2:3] offset:2048 sc0 sc1 nt
	global_load_dwordx4 v[84:87], v54, s[2:3] offset:3072 sc0 sc1 nt
	s_waitcnt vmcnt(0)
	v_mul_f32_e32 v2, s16, v56
	v_mul_f32_e32 v3, s16, v58
	v_mul_f32_e32 v4, s16, v60
	v_mul_f32_e32 v5, s16, v62
	v_mul_f32_e32 v6, s16, v64
	v_mul_f32_e32 v7, s16, v66
	v_mul_f32_e32 v8, s16, v68
	v_mul_f32_e32 v9, s16, v70
	v_mul_f32_e32 v10, s16, v72
	v_mul_f32_e32 v11, s16, v74
	v_mul_f32_e32 v12, s16, v76
	v_mul_f32_e32 v13, s16, v78
	v_mul_f32_e32 v14, s16, v80
	v_mul_f32_e32 v15, s16, v82
	v_mul_f32_e32 v16, s16, v84
	v_mul_f32_e32 v17, s16, v86
	v_mul_f32_e32 v18, s16, v57
	v_mul_f32_e32 v19, s16, v59
	v_mul_f32_e32 v20, s16, v61
	v_mul_f32_e32 v21, s16, v63
	v_mul_f32_e32 v22, s16, v65
	v_mul_f32_e32 v23, s16, v67
	v_mul_f32_e32 v24, s16, v69
	v_mul_f32_e32 v25, s16, v71
	v_mul_f32_e32 v26, s16, v73
	v_mul_f32_e32 v27, s16, v75
	v_mul_f32_e32 v28, s16, v77
	v_mul_f32_e32 v29, s16, v79
	v_mul_f32_e32 v30, s16, v81
	v_mul_f32_e32 v31, s16, v83
	v_mul_f32_e32 v32, s16, v85
	v_mul_f32_e32 v33, s16, v87
	s_nop 0
	v_cvt_scalef32_2xpk16_fp6_f32 v[40:45], v[2:17], v[18:33], 1.0
	global_load_dwordx4 v[56:59], v52, s[4:5] sc0 sc1 nt
	global_load_dwordx4 v[60:63], v52, s[4:5] offset:1024 sc0 sc1 nt
	global_load_dwordx4 v[64:67], v52, s[4:5] offset:2048 sc0 sc1 nt
	global_load_dwordx4 v[68:71], v52, s[4:5] offset:3072 sc0 sc1 nt
	global_load_dwordx4 v[72:75], v54, s[4:5] sc0 sc1 nt
	global_load_dwordx4 v[76:79], v54, s[4:5] offset:1024 sc0 sc1 nt
	global_load_dwordx4 v[80:83], v54, s[4:5] offset:2048 sc0 sc1 nt
	global_load_dwordx4 v[84:87], v54, s[4:5] offset:3072 sc0 sc1 nt
	s_waitcnt vmcnt(0)
	v_mul_f32_e32 v2, 4.0, v56
	v_mul_f32_e32 v3, 4.0, v58
	v_mul_f32_e32 v4, 4.0, v60
	v_mul_f32_e32 v5, 4.0, v62
	v_mul_f32_e32 v6, 4.0, v64
	v_mul_f32_e32 v7, 4.0, v66
	v_mul_f32_e32 v8, 4.0, v68
	v_mul_f32_e32 v9, 4.0, v70
	v_mul_f32_e32 v10, 4.0, v72
	v_mul_f32_e32 v11, 4.0, v74
	v_mul_f32_e32 v12, 4.0, v76
	v_mul_f32_e32 v13, 4.0, v78
	v_mul_f32_e32 v14, 4.0, v80
	v_mul_f32_e32 v15, 4.0, v82
	v_mul_f32_e32 v16, 4.0, v84
	v_mul_f32_e32 v17, 4.0, v86
	v_mul_f32_e32 v18, 4.0, v57
	v_mul_f32_e32 v19, 4.0, v59
	v_mul_f32_e32 v20, 4.0, v61
	v_mul_f32_e32 v21, 4.0, v63
	v_mul_f32_e32 v22, 4.0, v65
	v_mul_f32_e32 v23, 4.0, v67
	v_mul_f32_e32 v24, 4.0, v69
	v_mul_f32_e32 v25, 4.0, v71
	v_mul_f32_e32 v26, 4.0, v73
	v_mul_f32_e32 v27, 4.0, v75
	v_mul_f32_e32 v28, 4.0, v77
	v_mul_f32_e32 v29, 4.0, v79
	v_mul_f32_e32 v30, 4.0, v81
	v_mul_f32_e32 v31, 4.0, v83
	v_mul_f32_e32 v32, 4.0, v85
	v_mul_f32_e32 v33, 4.0, v87
	s_nop 0
	v_cvt_scalef32_2xpk16_fp6_f32 v[46:51], v[2:17], v[18:33], 1.0
	global_store_dwordx4 v53, v[40:43], s[6:7]
	global_store_dwordx4 v53, v[48:51], s[6:7] offset:1024
	global_store_dwordx4 v53, v[44:47], s[6:7] offset:2048
	s_add_u32 s6, s6, s13
	s_addc_u32 s7, s7, 0
	s_branch .Lenc_end_a

; __global__ void __launch_bounds__(256, 2) fwd_megakernel(Params p) {
;     ...
;   for (int jt = (bid >> 3); jt < 8 * 16; jt += (nb >> 3)) {
;     const int pn = jt >> 3, pm = (bid & 7) * 8 + (jt & 7);
;     const u16* A = p.h + (size_t)pm * 256 * 2048;
;     gemm_tile256([&](int r, int k) { return A + (size_t)r * 2048 + k; }, p.Wt_q + (size_t)pn * 128 * 2048, 2048, 2048,
;               [&](auto&& stager, int h) {
;                 u16* ot = p.pq + (size_t)(pm * 2 + h) * 128 * 2048 + pn * 128;
.Lenc_end_a:
	s_lshl_b32 s0, s94, 3
	s_lshr_b32 s2, s94, 3
	s_and_b32 s3, s0, 56
	s_ashr_i32 s4, s92, 3
	s_mov_b64 s[8:9], s[80:81]
	s_add_u32 s5, s8, 0x200000
	s_addc_u32 s10, s9, 0
	s_and_b32 s0, s94, 7
	s_lshl_b32 s11, s0, 22
	s_add_u32 s12, s50, 0x40000
	s_addc_u32 s13, s51, 0
	s_lshl_b32 s14, s0, 23
	v_mov_b32_e32 v131, 0
	s_movk_i32 s15, 0x4000
	s_movk_i32 s16, 0x210
	s_movk_i32 s17, 0x80
	s_mov_b32 s18, 0x10000
	s_mov_b32 s19, 0x20000
	s_mov_b32 s20, 0x30000
	s_mov_b32 s21, 0x80000
	s_mov_b32 s22, 0x90000
	s_mov_b32 s23, 0xa0000
	s_mov_b32 s24, 0xb0000

; DEV int ltid() { int t = threadIdx.x; asm volatile("" : "+v"(t)); return t; }
; DEV unsigned pack2(float a, float b) { float2v v = {a, b}; return __builtin_bit_cast(unsigned, __builtin_convertvector(v, bf16x2v)); }
; __global__ void __launch_bounds__(256, 2) fwd_megakernel(Params p) {
;     ...
;                 const int t2 = ltid(), c8 = t2 & 15, r0 = t2 >> 4;
; #pragma unroll 4
;                 for (int ps = 0; ps < 8; ++ps) {
;                   const int r = ps * 16 + r0;
;                   const float4 s0 = *(const float4*)(smf + r * 132 + c8 * 8), s1 = *(const float4*)(smf + r * 132 + c8 * 8 + 4);
;                   u32x4 o; o[0] = pack2(s0.x, s0.y); o[1] = pack2(s0.z, s0.w); o[2] = pack2(s1.x, s1.y); o[3] = pack2(s1.z, s1.w);
;                   *(u32x4*)(ot + (size_t)r * 2048 + c8 * 8) = o;
;                 }
;     ...
;   if (bid >= (nb >> 1)) {
;   for (size_t blk = (size_t)bid * 256 + tid; blk < (size_t)16384 * 64; blk += (size_t)nb * 256) {
; #pragma unroll
;     for (int tb = 0; tb < 2; ++tb) {
;       const float* src = (tb ? p.peer_up : p.peer_down) + blk * 32;
;       const float sc = tb ? UP_SCALE : DOWN_SCALE;
;       v16f va, vb;
; #pragma unroll
;       for (int q = 0; q < 4; ++q) {
;         const float4 x = *(const float4*)(src + q * 8), y = *(const float4*)(src + q * 8 + 4);
;         va[q * 4] = x.x * sc; vb[q * 4] = x.y * sc; va[q * 4 + 1] = x.z * sc; vb[q * 4 + 1] = x.w * sc;
;         va[q * 4 + 2] = y.x * sc; vb[q * 4 + 2] = y.y * sc; va[q * 4 + 3] = y.z * sc; vb[q * 4 + 3] = y.w * sc;
;       }
;       const v6u o = __builtin_amdgcn_cvt_scalef32_2xpk16_fp6_f32(va, vb, 1.0f);
;       unsigned char* dst = (tb ? p.up8 : p.down8) + blk * 24;
;       *(u32x2*)dst = u32x2{o[0], o[1]}; *(u32x2*)(dst + 8) = u32x2{o[2], o[3]}; *(u32x2*)(dst + 16) = u32x2{o[4], o[5]};
;     }
;   }
.LBB0_1382:
	v_lshl_add_u64 v[36:37], v[2:3], 0, s[0:1]
	v_add_co_u32_e32 v38, vcc, s21, v36
	ds_read_b128 v[4:7], v1
	ds_read_b128 v[8:11], v1 offset:16
	v_addc_co_u32_e32 v39, vcc, 0, v37, vcc
	ds_read_b128 v[12:15], v1 offset:8448
	ds_read_b128 v[16:19], v1 offset:8464
	ds_read_b128 v[20:23], v1 offset:16896
	ds_read_b128 v[24:27], v1 offset:16912
	ds_read_b128 v[28:31], v1 offset:25344
	ds_read_b128 v[32:35], v1 offset:25360
	v_add_co_u32_e32 v40, vcc, s22, v36
	s_add_u32 s0, s0, 0x40000
	s_nop 0
	v_addc_co_u32_e32 v41, vcc, 0, v37, vcc
	v_add_co_u32_e32 v42, vcc, s23, v36
	s_addc_u32 s1, s1, 0
	s_nop 0
	v_addc_co_u32_e32 v43, vcc, 0, v37, vcc
	v_add_u32_e32 v1, 0x8400, v1
	s_cmp_lg_u32 s0, 0x80000
	v_add_co_u32_e32 v36, vcc, s24, v36
	s_waitcnt lgkmcnt(7)
	v_cvt_pk_bf16_f32 v4, v4, v5
	v_cvt_pk_bf16_f32 v5, v6, v7
	s_waitcnt lgkmcnt(6)
	v_cvt_pk_bf16_f32 v6, v8, v9
	v_cvt_pk_bf16_f32 v7, v10, v11
	s_waitcnt lgkmcnt(5)
	v_cvt_pk_bf16_f32 v8, v12, v13
	v_cvt_pk_bf16_f32 v9, v14, v15
	s_waitcnt lgkmcnt(4)
	v_cvt_pk_bf16_f32 v10, v16, v17
	v_cvt_pk_bf16_f32 v11, v18, v19
	s_waitcnt lgkmcnt(3)
	v_cvt_pk_bf16_f32 v12, v20, v21
	v_cvt_pk_bf16_f32 v13, v22, v23
	s_waitcnt lgkmcnt(2)
	v_cvt_pk_bf16_f32 v14, v24, v25
	v_cvt_pk_bf16_f32 v15, v26, v27
	s_waitcnt lgkmcnt(1)
	v_cvt_pk_bf16_f32 v16, v28, v29
	v_cvt_pk_bf16_f32 v17, v30, v31
	s_waitcnt lgkmcnt(0)
	v_cvt_pk_bf16_f32 v18, v32, v33
	v_cvt_pk_bf16_f32 v19, v34, v35
	v_addc_co_u32_e32 v37, vcc, 0, v37, vcc
	global_store_dwordx4 v[38:39], v[4:7], off
	global_store_dwordx4 v[40:41], v[8:11], off
	global_store_dwordx4 v[42:43], v[12:15], off
	global_store_dwordx4 v[36:37], v[16:19], off
	s_cbranch_scc1 .LBB0_1382
	s_lshr_b32 s0, s92, 3
	s_add_i32 s58, s58, s4
	s_add_i32 s2, s2, s0
	s_cmpk_gt_i32 s58, 0x7f
	s_barrier
	s_cbranch_scc0 .LBB0_1367
	s_lshr_b32 s0, s92, 1
	s_cmp_ge_u32 s94, s0
	s_cbranch_scc0 .Lenc_end_b
	v_readlane_b32 s40, v254, 8
	v_readlane_b32 s41, v254, 9
	v_readlane_b32 s42, v254, 10
	v_readlane_b32 s43, v254, 11
	s_nop 4
	s_mov_b64 exec, -1
	v_lshrrev_b32_e32 v54, 6, v0
	v_and_b32_e32 v55, 63, v0
	v_lshlrev_b32_e32 v52, 13, v54
	v_lshl_or_b32 v52, v55, 4, v52
	v_mul_u32_u24_e32 v53, 0xc00, v54
	v_lshl_or_b32 v53, v55, 4, v53
	v_add_u32_e32 v54, 0x1000, v52
	s_lshl_b32 s10, s94, 8
	s_lshl_b32 s11, s92, 8
	s_lshl_b32 s12, s92, 15
	s_mul_i32 s13, s92, 0x3000
	s_mov_b32 s16, 0x42800000
	s_lshl_b32 s0, s94, 15
	s_add_u32 s2, s40, s0
	s_addc_u32 s3, s41, 0
	s_add_u32 s4, s42, s0
	s_addc_u32 s5, s43, 0
	s_mul_i32 s0, s94, 0x3000
	s_add_u32 s6, s62, s0
	s_addc_u32 s7, s63, 0
	s_cmp_lt_u32 s10, 0x100000
	s_cbranch_scc0 .Lenc_end_b
	s_cmpk_lg_u32 s92, 0x200
	s_cbranch_scc1 .Lenc_generic_b
	global_load_dwordx4 v[56:59], v52, s[2:3] sc0 sc1 nt
	global_load_dwordx4 v[60:63], v52, s[2:3] offset:1024 sc0 sc1 nt
	global_load_dwordx4 v[64:67], v52, s[2:3] offset:2048 sc0 sc1 nt
	global_load_dwordx4 v[68:71], v52, s[2:3] offset:3072 sc0 sc1 nt
	global_load_dwordx4 v[72:75], v54, s[2:3] sc0 sc1 nt
	global_load_dwordx4 v[76:79], v54, s[2:3] offset:1024 sc0 sc1 nt
	global_load_dwordx4 v[80:83], v54, s[2:3] offset:2048 sc0 sc1 nt
	global_load_dwordx4 v[84:87], v54, s[2:3] offset:3072 sc0 sc1 nt
	s_waitcnt vmcnt(0)
	v_mul_f32_e32 v2, s16, v56
	v_mul_f32_e32 v3, s16, v58
	v_mul_f32_e32 v4, s16, v60
	v_mul_f32_e32 v5, s16, v62
	v_mul_f32_e32 v6, s16, v64
	v_mul_f32_e32 v7, s16, v66
	v_mul_f32_e32 v8, s16, v68
	v_mul_f32_e32 v9, s16, v70
	v_mul_f32_e32 v10, s16, v72
	v_mul_f32_e32 v11, s16, v74
	v_mul_f32_e32 v12, s16, v76
	v_mul_f32_e32 v13, s16, v78
	v_mul_f32_e32 v14, s16, v80
	v_mul_f32_e32 v15, s16, v82
	v_mul_f32_e32 v16, s16, v84
	v_mul_f32_e32 v17, s16, v86
	v_mul_f32_e32 v18, s16, v57
	v_mul_f32_e32 v19, s16, v59
	v_mul_f32_e32 v20, s16, v61
	v_mul_f32_e32 v21, s16, v63
	v_mul_f32_e32 v22, s16, v65
	v_mul_f32_e32 v23, s16, v67
	v_mul_f32_e32 v24, s16, v69
	v_mul_f32_e32 v25, s16, v71
	v_mul_f32_e32 v26, s16, v73
	v_mul_f32_e32 v27, s16, v75
	v_mul_f32_e32 v28, s16, v77
	v_mul_f32_e32 v29, s16, v79
	v_mul_f32_e32 v30, s16, v81
	v_mul_f32_e32 v31, s16, v83
	v_mul_f32_e32 v32, s16, v85
	v_mul_f32_e32 v33, s16, v87
	s_nop 0
	v_cvt_scalef32_2xpk16_fp6_f32 v[40:45], v[2:17], v[18:33], 1.0
	global_load_dwordx4 v[56:59], v52, s[4:5] sc0 sc1 nt
	global_load_dwordx4 v[60:63], v52, s[4:5] offset:1024 sc0 sc1 nt
	global_load_dwordx4 v[64:67], v52, s[4:5] offset:2048 sc0 sc1 nt
	global_load_dwordx4 v[68:71], v52, s[4:5] offset:3072 sc0 sc1 nt
	global_load_dwordx4 v[72:75], v54, s[4:5] sc0 sc1 nt
	global_load_dwordx4 v[76:79], v54, s[4:5] offset:1024 sc0 sc1 nt
	global_load_dwordx4 v[80:83], v54, s[4:5] offset:2048 sc0 sc1 nt
	global_load_dwordx4 v[84:87], v54, s[4:5] offset:3072 sc0 sc1 nt
	s_add_u32 s2, s2, s12
	s_addc_u32 s3, s3, 0
	s_add_u32 s4, s4, s12
	s_addc_u32 s5, s5, 0
	s_waitcnt vmcnt(0)
; __global__ void __launch_bounds__(256, 2) fwd_megakernel(Params p) {
;     ...
;   if (bid >= (nb >> 1)) {
;   for (size_t blk = (size_t)bid * 256 + tid; blk < (size_t)16384 * 64; blk += (size_t)nb * 256) {
; #pragma unroll
;     for (int tb = 0; tb < 2; ++tb) {
;       const float* src = (tb ? p.peer_up : p.peer_down) + blk * 32;
;       const float sc = tb ? UP_SCALE : DOWN_SCALE;
;       v16f va, vb;
; #pragma unroll
;       for (int q = 0; q < 4; ++q) {
;         const float4 x = *(const float4*)(src + q * 8), y = *(const float4*)(src + q * 8 + 4);
;         va[q * 4] = x.x * sc; vb[q * 4] = x.y * sc; va[q * 4 + 1] = x.z * sc; vb[q * 4 + 1] = x.w * sc;
;         va[q * 4 + 2] = y.x * sc; vb[q * 4 + 2] = y.y * sc; va[q * 4 + 3] = y.z * sc; vb[q * 4 + 3] = y.w * sc;
;       }
;       const v6u o = __builtin_amdgcn_cvt_scalef32_2xpk16_fp6_f32(va, vb, 1.0f);
;       unsigned char* dst = (tb ? p.up8 : p.down8) + blk * 24;
;       *(u32x2*)dst = u32x2{o[0], o[1]}; *(u32x2*)(dst + 8) = u32x2{o[2], o[3]}; *(u32x2*)(dst + 16) = u32x2{o[4], o[5]};
;     }
;   }
	v_mul_f32_e32 v2, 4.0, v56
	v_mul_f32_e32 v3, 4.0, v58
	v_mul_f32_e32 v4, 4.0, v60
	v_mul_f32_e32 v5, 4.0, v62
	v_mul_f32_e32 v6, 4.0, v64
	v_mul_f32_e32 v7, 4.0, v66
	v_mul_f32_e32 v8, 4.0, v68
	v_mul_f32_e32 v9, 4.0, v70
	v_mul_f32_e32 v10, 4.0, v72
	v_mul_f32_e32 v11, 4.0, v74
	v_mul_f32_e32 v12, 4.0, v76
	v_mul_f32_e32 v13, 4.0, v78
	v_mul_f32_e32 v14, 4.0, v80
	v_mul_f32_e32 v15, 4.0, v82
	v_mul_f32_e32 v16, 4.0, v84
	v_mul_f32_e32 v17, 4.0, v86
	v_mul_f32_e32 v18, 4.0, v57
	v_mul_f32_e32 v19, 4.0, v59
	v_mul_f32_e32 v20, 4.0, v61
	v_mul_f32_e32 v21, 4.0, v63
	v_mul_f32_e32 v22, 4.0, v65
	v_mul_f32_e32 v23, 4.0, v67
	v_mul_f32_e32 v24, 4.0, v69
	v_mul_f32_e32 v25, 4.0, v71
	v_mul_f32_e32 v26, 4.0, v73
	v_mul_f32_e32 v27, 4.0, v75
	v_mul_f32_e32 v28, 4.0, v77
	v_mul_f32_e32 v29, 4.0, v79
	v_mul_f32_e32 v30, 4.0, v81
	v_mul_f32_e32 v31, 4.0, v83
	v_mul_f32_e32 v32, 4.0, v85
	v_mul_f32_e32 v33, 4.0, v87
	s_nop 0
	v_cvt_scalef32_2xpk16_fp6_f32 v[46:51], v[2:17], v[18:33], 1.0
	global_store_dwordx4 v53, v[40:43], s[6:7]
	global_store_dwordx4 v53, v[48:51], s[6:7] offset:1024
	global_store_dwordx4 v53, v[44:47], s[6:7] offset:2048
	s_add_u32 s6, s6, s13
	s_addc_u32 s7, s7, 0
	global_load_dwordx4 v[56:59], v52, s[2:3] sc0 sc1 nt
	global_load_dwordx4 v[60:63], v52, s[2:3] offset:1024 sc0 sc1 nt
	global_load_dwordx4 v[64:67], v52, s[2:3] offset:2048 sc0 sc1 nt
	global_load_dwordx4 v[68:71], v52, s[2:3] offset:3072 sc0 sc1 nt
	global_load_dwordx4 v[72:75], v54, s[2:3] sc0 sc1 nt
	global_load_dwordx4 v[76:79], v54, s[2:3] offset:1024 sc0 sc1 nt
	global_load_dwordx4 v[80:83], v54, s[2:3] offset:2048 sc0 sc1 nt
	global_load_dwordx4 v[84:87], v54, s[2:3] offset:3072 sc0 sc1 nt
	s_waitcnt vmcnt(0)
	v_mul_f32_e32 v2, s16, v56
	v_mul_f32_e32 v3, s16, v58
	v_mul_f32_e32 v4, s16, v60
	v_mul_f32_e32 v5, s16, v62
	v_mul_f32_e32 v6, s16, v64
	v_mul_f32_e32 v7, s16, v66
	v_mul_f32_e32 v8, s16, v68
	v_mul_f32_e32 v9, s16, v70
	v_mul_f32_e32 v10, s16, v72
	v_mul_f32_e32 v11, s16, v74
	v_mul_f32_e32 v12, s16, v76
	v_mul_f32_e32 v13, s16, v78
	v_mul_f32_e32 v14, s16, v80
	v_mul_f32_e32 v15, s16, v82
	v_mul_f32_e32 v16, s16, v84
	v_mul_f32_e32 v17, s16, v86
	v_mul_f32_e32 v18, s16, v57
	v_mul_f32_e32 v19, s16, v59
	v_mul_f32_e32 v20, s16, v61
	v_mul_f32_e32 v21, s16, v63
	v_mul_f32_e32 v22, s16, v65
	v_mul_f32_e32 v23, s16, v67
	v_mul_f32_e32 v24, s16, v69
	v_mul_f32_e32 v25, s16, v71
	v_mul_f32_e32 v26, s16, v73
	v_mul_f32_e32 v27, s16, v75
	v_mul_f32_e32 v28, s16, v77
	v_mul_f32_e32 v29, s16, v79
	v_mul_f32_e32 v30, s16, v81
	v_mul_f32_e32 v31, s16, v83
	v_mul_f32_e32 v32, s16, v85
	v_mul_f32_e32 v33, s16, v87
	s_nop 0
	v_cvt_scalef32_2xpk16_fp6_f32 v[40:45], v[2:17], v[18:33], 1.0
	global_load_dwordx4 v[56:59], v52, s[4:5] sc0 sc1 nt
	global_load_dwordx4 v[60:63], v52, s[4:5] offset:1024 sc0 sc1 nt
	global_load_dwordx4 v[64:67], v52, s[4:5] offset:2048 sc0 sc1 nt
	global_load_dwordx4 v[68:71], v52, s[4:5] offset:3072 sc0 sc1 nt
	global_load_dwordx4 v[72:75], v54, s[4:5] sc0 sc1 nt
	global_load_dwordx4 v[76:79], v54, s[4:5] offset:1024 sc0 sc1 nt
	global_load_dwordx4 v[80:83], v54, s[4:5] offset:2048 sc0 sc1 nt
	global_load_dwordx4 v[84:87], v54, s[4:5] offset:3072 sc0 sc1 nt
	s_add_u32 s2, s2, s12
	s_addc_u32 s3, s3, 0
	s_add_u32 s4, s4, s12
	s_addc_u32 s5, s5, 0
	s_waitcnt vmcnt(0)
	v_mul_f32_e32 v2, 4.0, v56
	v_mul_f32_e32 v3, 4.0, v58
	v_mul_f32_e32 v4, 4.0, v60
	v_mul_f32_e32 v5, 4.0, v62
	v_mul_f32_e32 v6, 4.0, v64
	v_mul_f32_e32 v7, 4.0, v66
	v_mul_f32_e32 v8, 4.0, v68
	v_mul_f32_e32 v9, 4.0, v70
	v_mul_f32_e32 v10, 4.0, v72
	v_mul_f32_e32 v11, 4.0, v74
	v_mul_f32_e32 v12, 4.0, v76
	v_mul_f32_e32 v13, 4.0, v78
	v_mul_f32_e32 v14, 4.0, v80
	v_mul_f32_e32 v15, 4.0, v82
	v_mul_f32_e32 v16, 4.0, v84
	v_mul_f32_e32 v17, 4.0, v86
	v_mul_f32_e32 v18, 4.0, v57
	v_mul_f32_e32 v19, 4.0, v59
	v_mul_f32_e32 v20, 4.0, v61
	v_mul_f32_e32 v21, 4.0, v63
	v_mul_f32_e32 v22, 4.0, v65
	v_mul_f32_e32 v23, 4.0, v67
	v_mul_f32_e32 v24, 4.0, v69
	v_mul_f32_e32 v25, 4.0, v71
	v_mul_f32_e32 v26, 4.0, v73
	v_mul_f32_e32 v27, 4.0, v75
	v_mul_f32_e32 v28, 4.0, v77
	v_mul_f32_e32 v29, 4.0, v79
	v_mul_f32_e32 v30, 4.0, v81
	v_mul_f32_e32 v31, 4.0, v83
	v_mul_f32_e32 v32, 4.0, v85
	v_mul_f32_e32 v33, 4.0, v87
	s_nop 0
	v_cvt_scalef32_2xpk16_fp6_f32 v[46:51], v[2:17], v[18:33], 1.0
	global_store_dwordx4 v53, v[40:43], s[6:7]
	global_store_dwordx4 v53, v[48:51], s[6:7] offset:1024
	global_store_dwordx4 v53, v[44:47], s[6:7] offset:2048
	s_add_u32 s6, s6, s13
	s_addc_u32 s7, s7, 0
	global_load_dwordx4 v[56:59], v52, s[2:3] sc0 sc1 nt
	global_load_dwordx4 v[60:63], v52, s[2:3] offset:1024 sc0 sc1 nt
	global_load_dwordx4 v[64:67], v52, s[2:3] offset:2048 sc0 sc1 nt
	global_load_dwordx4 v[68:71], v52, s[2:3] offset:3072 sc0 sc1 nt
	global_load_dwordx4 v[72:75], v54, s[2:3] sc0 sc1 nt
	global_load_dwordx4 v[76:79], v54, s[2:3] offset:1024 sc0 sc1 nt
	global_load_dwordx4 v[80:83], v54, s[2:3] offset:2048 sc0 sc1 nt
	global_load_dwordx4 v[84:87], v54, s[2:3] offset:3072 sc0 sc1 nt
	s_waitcnt vmcnt(0)
; __global__ void __launch_bounds__(256, 2) fwd_megakernel(Params p) {
;     ...
;   if (bid >= (nb >> 1)) {
;   for (size_t blk = (size_t)bid * 256 + tid; blk < (size_t)16384 * 64; blk += (size_t)nb * 256) {
; #pragma unroll
;     for (int tb = 0; tb < 2; ++tb) {
;       const float* src = (tb ? p.peer_up : p.peer_down) + blk * 32;
;       const float sc = tb ? UP_SCALE : DOWN_SCALE;
;       v16f va, vb;
; #pragma unroll
;       for (int q = 0; q < 4; ++q) {
;         const float4 x = *(const float4*)(src + q * 8), y = *(const float4*)(src + q * 8 + 4);
;         va[q * 4] = x.x * sc; vb[q * 4] = x.y * sc; va[q * 4 + 1] = x.z * sc; vb[q * 4 + 1] = x.w * sc;
;         va[q * 4 + 2] = y.x * sc; vb[q * 4 + 2] = y.y * sc; va[q * 4 + 3] = y.z * sc; vb[q * 4 + 3] = y.w * sc;
;       }
;       const v6u o = __builtin_amdgcn_cvt_scalef32_2xpk16_fp6_f32(va, vb, 1.0f);
;       unsigned char* dst = (tb ? p.up8 : p.down8) + blk * 24;
;       *(u32x2*)dst = u32x2{o[0], o[1]}; *(u32x2*)(dst + 8) = u32x2{o[2], o[3]}; *(u32x2*)(dst + 16) = u32x2{o[4], o[5]};
;     }
;   }
	v_mul_f32_e32 v2, s16, v56
	v_mul_f32_e32 v3, s16, v58
	v_mul_f32_e32 v4, s16, v60
	v_mul_f32_e32 v5, s16, v62
	v_mul_f32_e32 v6, s16, v64
	v_mul_f32_e32 v7, s16, v66
	v_mul_f32_e32 v8, s16, v68
	v_mul_f32_e32 v9, s16, v70
	v_mul_f32_e32 v10, s16, v72
	v_mul_f32_e32 v11, s16, v74
	v_mul_f32_e32 v12, s16, v76
	v_mul_f32_e32 v13, s16, v78
	v_mul_f32_e32 v14, s16, v80
	v_mul_f32_e32 v15, s16, v82
	v_mul_f32_e32 v16, s16, v84
	v_mul_f32_e32 v17, s16, v86
	v_mul_f32_e32 v18, s16, v57
	v_mul_f32_e32 v19, s16, v59
	v_mul_f32_e32 v20, s16, v61
	v_mul_f32_e32 v21, s16, v63
	v_mul_f32_e32 v22, s16, v65
	v_mul_f32_e32 v23, s16, v67
	v_mul_f32_e32 v24, s16, v69
	v_mul_f32_e32 v25, s16, v71
	v_mul_f32_e32 v26, s16, v73
	v_mul_f32_e32 v27, s16, v75
	v_mul_f32_e32 v28, s16, v77
	v_mul_f32_e32 v29, s16, v79
	v_mul_f32_e32 v30, s16, v81
	v_mul_f32_e32 v31, s16, v83
	v_mul_f32_e32 v32, s16, v85
	v_mul_f32_e32 v33, s16, v87
	s_nop 0
	v_cvt_scalef32_2xpk16_fp6_f32 v[40:45], v[2:17], v[18:33], 1.0
	global_load_dwordx4 v[56:59], v52, s[4:5] sc0 sc1 nt
	global_load_dwordx4 v[60:63], v52, s[4:5] offset:1024 sc0 sc1 nt
	global_load_dwordx4 v[64:67], v52, s[4:5] offset:2048 sc0 sc1 nt
	global_load_dwordx4 v[68:71], v52, s[4:5] offset:3072 sc0 sc1 nt
	global_load_dwordx4 v[72:75], v54, s[4:5] sc0 sc1 nt
	global_load_dwordx4 v[76:79], v54, s[4:5] offset:1024 sc0 sc1 nt
	global_load_dwordx4 v[80:83], v54, s[4:5] offset:2048 sc0 sc1 nt
	global_load_dwordx4 v[84:87], v54, s[4:5] offset:3072 sc0 sc1 nt
	s_add_u32 s2, s2, s12
	s_addc_u32 s3, s3, 0
	s_add_u32 s4, s4, s12
	s_addc_u32 s5, s5, 0
	s_waitcnt vmcnt(0)
	v_mul_f32_e32 v2, 4.0, v56
	v_mul_f32_e32 v3, 4.0, v58
	v_mul_f32_e32 v4, 4.0, v60
	v_mul_f32_e32 v5, 4.0, v62
	v_mul_f32_e32 v6, 4.0, v64
	v_mul_f32_e32 v7, 4.0, v66
	v_mul_f32_e32 v8, 4.0, v68
	v_mul_f32_e32 v9, 4.0, v70
	v_mul_f32_e32 v10, 4.0, v72
	v_mul_f32_e32 v11, 4.0, v74
	v_mul_f32_e32 v12, 4.0, v76
	v_mul_f32_e32 v13, 4.0, v78
	v_mul_f32_e32 v14, 4.0, v80
	v_mul_f32_e32 v15, 4.0, v82
	v_mul_f32_e32 v16, 4.0, v84
	v_mul_f32_e32 v17, 4.0, v86
	v_mul_f32_e32 v18, 4.0, v57
	v_mul_f32_e32 v19, 4.0, v59
	v_mul_f32_e32 v20, 4.0, v61
	v_mul_f32_e32 v21, 4.0, v63
	v_mul_f32_e32 v22, 4.0, v65
	v_mul_f32_e32 v23, 4.0, v67
	v_mul_f32_e32 v24, 4.0, v69
	v_mul_f32_e32 v25, 4.0, v71
	v_mul_f32_e32 v26, 4.0, v73
	v_mul_f32_e32 v27, 4.0, v75
	v_mul_f32_e32 v28, 4.0, v77
	v_mul_f32_e32 v29, 4.0, v79
	v_mul_f32_e32 v30, 4.0, v81
	v_mul_f32_e32 v31, 4.0, v83
	v_mul_f32_e32 v32, 4.0, v85
	v_mul_f32_e32 v33, 4.0, v87
	s_nop 0
	v_cvt_scalef32_2xpk16_fp6_f32 v[46:51], v[2:17], v[18:33], 1.0
	global_store_dwordx4 v53, v[40:43], s[6:7]
	global_store_dwordx4 v53, v[48:51], s[6:7] offset:1024
	global_store_dwordx4 v53, v[44:47], s[6:7] offset:2048
	s_add_u32 s6, s6, s13
	s_addc_u32 s7, s7, 0
	global_load_dwordx4 v[56:59], v52, s[2:3] sc0 sc1 nt
	global_load_dwordx4 v[60:63], v52, s[2:3] offset:1024 sc0 sc1 nt
	global_load_dwordx4 v[64:67], v52, s[2:3] offset:2048 sc0 sc1 nt
	global_load_dwordx4 v[68:71], v52, s[2:3] offset:3072 sc0 sc1 nt
	global_load_dwordx4 v[72:75], v54, s[2:3] sc0 sc1 nt
	global_load_dwordx4 v[76:79], v54, s[2:3] offset:1024 sc0 sc1 nt
	global_load_dwordx4 v[80:83], v54, s[2:3] offset:2048 sc0 sc1 nt
	global_load_dwordx4 v[84:87], v54, s[2:3] offset:3072 sc0 sc1 nt
	s_waitcnt vmcnt(0)
	v_mul_f32_e32 v2, s16, v56
	v_mul_f32_e32 v3, s16, v58
	v_mul_f32_e32 v4, s16, v60
	v_mul_f32_e32 v5, s16, v62
	v_mul_f32_e32 v6, s16, v64
	v_mul_f32_e32 v7, s16, v66
	v_mul_f32_e32 v8, s16, v68
	v_mul_f32_e32 v9, s16, v70
	v_mul_f32_e32 v10, s16, v72
	v_mul_f32_e32 v11, s16, v74
	v_mul_f32_e32 v12, s16, v76
	v_mul_f32_e32 v13, s16, v78
	v_mul_f32_e32 v14, s16, v80
	v_mul_f32_e32 v15, s16, v82
	v_mul_f32_e32 v16, s16, v84
	v_mul_f32_e32 v17, s16, v86
	v_mul_f32_e32 v18, s16, v57
	v_mul_f32_e32 v19, s16, v59
	v_mul_f32_e32 v20, s16, v61
	v_mul_f32_e32 v21, s16, v63
	v_mul_f32_e32 v22, s16, v65
	v_mul_f32_e32 v23, s16, v67
	v_mul_f32_e32 v24, s16, v69
	v_mul_f32_e32 v25, s16, v71
	v_mul_f32_e32 v26, s16, v73
	v_mul_f32_e32 v27, s16, v75
	v_mul_f32_e32 v28, s16, v77
	v_mul_f32_e32 v29, s16, v79
	v_mul_f32_e32 v30, s16, v81
	v_mul_f32_e32 v31, s16, v83
	v_mul_f32_e32 v32, s16, v85
	v_mul_f32_e32 v33, s16, v87
	s_nop 0
	v_cvt_scalef32_2xpk16_fp6_f32 v[40:45], v[2:17], v[18:33], 1.0
	global_load_dwordx4 v[56:59], v52, s[4:5] sc0 sc1 nt
	global_load_dwordx4 v[60:63], v52, s[4:5] offset:1024 sc0 sc1 nt
	global_load_dwordx4 v[64:67], v52, s[4:5] offset:2048 sc0 sc1 nt
	global_load_dwordx4 v[68:71], v52, s[4:5] offset:3072 sc0 sc1 nt
	global_load_dwordx4 v[72:75], v54, s[4:5] sc0 sc1 nt
	global_load_dwordx4 v[76:79], v54, s[4:5] offset:1024 sc0 sc1 nt
	global_load_dwordx4 v[80:83], v54, s[4:5] offset:2048 sc0 sc1 nt
	global_load_dwordx4 v[84:87], v54, s[4:5] offset:3072 sc0 sc1 nt
	s_add_u32 s2, s2, s12
	s_addc_u32 s3, s3, 0
	s_add_u32 s4, s4, s12
	s_addc_u32 s5, s5, 0
	s_waitcnt vmcnt(0)
; __global__ void __launch_bounds__(256, 2) fwd_megakernel(Params p) {
;     ...
;   if (bid >= (nb >> 1)) {
;   for (size_t blk = (size_t)bid * 256 + tid; blk < (size_t)16384 * 64; blk += (size_t)nb * 256) {
; #pragma unroll
;     for (int tb = 0; tb < 2; ++tb) {
;       const float* src = (tb ? p.peer_up : p.peer_down) + blk * 32;
;       const float sc = tb ? UP_SCALE : DOWN_SCALE;
;       v16f va, vb;
; #pragma unroll
;       for (int q = 0; q < 4; ++q) {
;         const float4 x = *(const float4*)(src + q * 8), y = *(const float4*)(src + q * 8 + 4);
;         va[q * 4] = x.x * sc; vb[q * 4] = x.y * sc; va[q * 4 + 1] = x.z * sc; vb[q * 4 + 1] = x.w * sc;
;         va[q * 4 + 2] = y.x * sc; vb[q * 4 + 2] = y.y * sc; va[q * 4 + 3] = y.z * sc; vb[q * 4 + 3] = y.w * sc;
;       }
;       const v6u o = __builtin_amdgcn_cvt_scalef32_2xpk16_fp6_f32(va, vb, 1.0f);
;       unsigned char* dst = (tb ? p.up8 : p.down8) + blk * 24;
;       *(u32x2*)dst = u32x2{o[0], o[1]}; *(u32x2*)(dst + 8) = u32x2{o[2], o[3]}; *(u32x2*)(dst + 16) = u32x2{o[4], o[5]};
;     }
;   }
	v_mul_f32_e32 v2, 4.0, v56
	v_mul_f32_e32 v3, 4.0, v58
	v_mul_f32_e32 v4, 4.0, v60
	v_mul_f32_e32 v5, 4.0, v62
	v_mul_f32_e32 v6, 4.0, v64
	v_mul_f32_e32 v7, 4.0, v66
	v_mul_f32_e32 v8, 4.0, v68
	v_mul_f32_e32 v9, 4.0, v70
	v_mul_f32_e32 v10, 4.0, v72
	v_mul_f32_e32 v11, 4.0, v74
	v_mul_f32_e32 v12, 4.0, v76
	v_mul_f32_e32 v13, 4.0, v78
	v_mul_f32_e32 v14, 4.0, v80
	v_mul_f32_e32 v15, 4.0, v82
	v_mul_f32_e32 v16, 4.0, v84
	v_mul_f32_e32 v17, 4.0, v86
	v_mul_f32_e32 v18, 4.0, v57
	v_mul_f32_e32 v19, 4.0, v59
	v_mul_f32_e32 v20, 4.0, v61
	v_mul_f32_e32 v21, 4.0, v63
	v_mul_f32_e32 v22, 4.0, v65
	v_mul_f32_e32 v23, 4.0, v67
	v_mul_f32_e32 v24, 4.0, v69
	v_mul_f32_e32 v25, 4.0, v71
	v_mul_f32_e32 v26, 4.0, v73
	v_mul_f32_e32 v27, 4.0, v75
	v_mul_f32_e32 v28, 4.0, v77
	v_mul_f32_e32 v29, 4.0, v79
	v_mul_f32_e32 v30, 4.0, v81
	v_mul_f32_e32 v31, 4.0, v83
	v_mul_f32_e32 v32, 4.0, v85
	v_mul_f32_e32 v33, 4.0, v87
	s_nop 0
	v_cvt_scalef32_2xpk16_fp6_f32 v[46:51], v[2:17], v[18:33], 1.0
	global_store_dwordx4 v53, v[40:43], s[6:7]
	global_store_dwordx4 v53, v[48:51], s[6:7] offset:1024
	global_store_dwordx4 v53, v[44:47], s[6:7] offset:2048
	s_add_u32 s6, s6, s13
	s_addc_u32 s7, s7, 0
	global_load_dwordx4 v[56:59], v52, s[2:3] sc0 sc1 nt
	global_load_dwordx4 v[60:63], v52, s[2:3] offset:1024 sc0 sc1 nt
	global_load_dwordx4 v[64:67], v52, s[2:3] offset:2048 sc0 sc1 nt
	global_load_dwordx4 v[68:71], v52, s[2:3] offset:3072 sc0 sc1 nt
	global_load_dwordx4 v[72:75], v54, s[2:3] sc0 sc1 nt
	global_load_dwordx4 v[76:79], v54, s[2:3] offset:1024 sc0 sc1 nt
	global_load_dwordx4 v[80:83], v54, s[2:3] offset:2048 sc0 sc1 nt
	global_load_dwordx4 v[84:87], v54, s[2:3] offset:3072 sc0 sc1 nt
	s_waitcnt vmcnt(0)
	v_mul_f32_e32 v2, s16, v56
	v_mul_f32_e32 v3, s16, v58
	v_mul_f32_e32 v4, s16, v60
	v_mul_f32_e32 v5, s16, v62
	v_mul_f32_e32 v6, s16, v64
	v_mul_f32_e32 v7, s16, v66
	v_mul_f32_e32 v8, s16, v68
	v_mul_f32_e32 v9, s16, v70
	v_mul_f32_e32 v10, s16, v72
	v_mul_f32_e32 v11, s16, v74
	v_mul_f32_e32 v12, s16, v76
	v_mul_f32_e32 v13, s16, v78
	v_mul_f32_e32 v14, s16, v80
	v_mul_f32_e32 v15, s16, v82
	v_mul_f32_e32 v16, s16, v84
	v_mul_f32_e32 v17, s16, v86
	v_mul_f32_e32 v18, s16, v57
	v_mul_f32_e32 v19, s16, v59
	v_mul_f32_e32 v20, s16, v61
	v_mul_f32_e32 v21, s16, v63
	v_mul_f32_e32 v22, s16, v65
	v_mul_f32_e32 v23, s16, v67
	v_mul_f32_e32 v24, s16, v69
	v_mul_f32_e32 v25, s16, v71
	v_mul_f32_e32 v26, s16, v73
	v_mul_f32_e32 v27, s16, v75
	v_mul_f32_e32 v28, s16, v77
	v_mul_f32_e32 v29, s16, v79
	v_mul_f32_e32 v30, s16, v81
	v_mul_f32_e32 v31, s16, v83
	v_mul_f32_e32 v32, s16, v85
	v_mul_f32_e32 v33, s16, v87
	s_nop 0
	v_cvt_scalef32_2xpk16_fp6_f32 v[40:45], v[2:17], v[18:33], 1.0
	global_load_dwordx4 v[56:59], v52, s[4:5] sc0 sc1 nt
	global_load_dwordx4 v[60:63], v52, s[4:5] offset:1024 sc0 sc1 nt
	global_load_dwordx4 v[64:67], v52, s[4:5] offset:2048 sc0 sc1 nt
	global_load_dwordx4 v[68:71], v52, s[4:5] offset:3072 sc0 sc1 nt
	global_load_dwordx4 v[72:75], v54, s[4:5] sc0 sc1 nt
	global_load_dwordx4 v[76:79], v54, s[4:5] offset:1024 sc0 sc1 nt
	global_load_dwordx4 v[80:83], v54, s[4:5] offset:2048 sc0 sc1 nt
	global_load_dwordx4 v[84:87], v54, s[4:5] offset:3072 sc0 sc1 nt
	s_add_u32 s2, s2, s12
	s_addc_u32 s3, s3, 0
	s_add_u32 s4, s4, s12
	s_addc_u32 s5, s5, 0
	s_waitcnt vmcnt(0)
	v_mul_f32_e32 v2, 4.0, v56
	v_mul_f32_e32 v3, 4.0, v58
	v_mul_f32_e32 v4, 4.0, v60
	v_mul_f32_e32 v5, 4.0, v62
	v_mul_f32_e32 v6, 4.0, v64
	v_mul_f32_e32 v7, 4.0, v66
	v_mul_f32_e32 v8, 4.0, v68
	v_mul_f32_e32 v9, 4.0, v70
	v_mul_f32_e32 v10, 4.0, v72
	v_mul_f32_e32 v11, 4.0, v74
	v_mul_f32_e32 v12, 4.0, v76
	v_mul_f32_e32 v13, 4.0, v78
	v_mul_f32_e32 v14, 4.0, v80
	v_mul_f32_e32 v15, 4.0, v82
	v_mul_f32_e32 v16, 4.0, v84
	v_mul_f32_e32 v17, 4.0, v86
	v_mul_f32_e32 v18, 4.0, v57
	v_mul_f32_e32 v19, 4.0, v59
	v_mul_f32_e32 v20, 4.0, v61
	v_mul_f32_e32 v21, 4.0, v63
	v_mul_f32_e32 v22, 4.0, v65
	v_mul_f32_e32 v23, 4.0, v67
	v_mul_f32_e32 v24, 4.0, v69
	v_mul_f32_e32 v25, 4.0, v71
	v_mul_f32_e32 v26, 4.0, v73
	v_mul_f32_e32 v27, 4.0, v75
	v_mul_f32_e32 v28, 4.0, v77
	v_mul_f32_e32 v29, 4.0, v79
	v_mul_f32_e32 v30, 4.0, v81
	v_mul_f32_e32 v31, 4.0, v83
	v_mul_f32_e32 v32, 4.0, v85
	v_mul_f32_e32 v33, 4.0, v87
	s_nop 0
	v_cvt_scalef32_2xpk16_fp6_f32 v[46:51], v[2:17], v[18:33], 1.0
	global_store_dwordx4 v53, v[40:43], s[6:7]
	global_store_dwordx4 v53, v[48:51], s[6:7] offset:1024
	global_store_dwordx4 v53, v[44:47], s[6:7] offset:2048
	s_add_u32 s6, s6, s13
	s_addc_u32 s7, s7, 0
	global_load_dwordx4 v[56:59], v52, s[2:3] sc0 sc1 nt
	global_load_dwordx4 v[60:63], v52, s[2:3] offset:1024 sc0 sc1 nt
	global_load_dwordx4 v[64:67], v52, s[2:3] offset:2048 sc0 sc1 nt
	global_load_dwordx4 v[68:71], v52, s[2:3] offset:3072 sc0 sc1 nt
	global_load_dwordx4 v[72:75], v54, s[2:3] sc0 sc1 nt
	global_load_dwordx4 v[76:79], v54, s[2:3] offset:1024 sc0 sc1 nt
	global_load_dwordx4 v[80:83], v54, s[2:3] offset:2048 sc0 sc1 nt
	global_load_dwordx4 v[84:87], v54, s[2:3] offset:3072 sc0 sc1 nt
	s_waitcnt vmcnt(0)
; __global__ void __launch_bounds__(256, 2) fwd_megakernel(Params p) {
;     ...
;   if (bid >= (nb >> 1)) {
;   for (size_t blk = (size_t)bid * 256 + tid; blk < (size_t)16384 * 64; blk += (size_t)nb * 256) {
; #pragma unroll
;     for (int tb = 0; tb < 2; ++tb) {
;       const float* src = (tb ? p.peer_up : p.peer_down) + blk * 32;
;       const float sc = tb ? UP_SCALE : DOWN_SCALE;
;       v16f va, vb;
; #pragma unroll
;       for (int q = 0; q < 4; ++q) {
;         const float4 x = *(const float4*)(src + q * 8), y = *(const float4*)(src + q * 8 + 4);
;         va[q * 4] = x.x * sc; vb[q * 4] = x.y * sc; va[q * 4 + 1] = x.z * sc; vb[q * 4 + 1] = x.w * sc;
;         va[q * 4 + 2] = y.x * sc; vb[q * 4 + 2] = y.y * sc; va[q * 4 + 3] = y.z * sc; vb[q * 4 + 3] = y.w * sc;
;       }
;       const v6u o = __builtin_amdgcn_cvt_scalef32_2xpk16_fp6_f32(va, vb, 1.0f);
;       unsigned char* dst = (tb ? p.up8 : p.down8) + blk * 24;
;       *(u32x2*)dst = u32x2{o[0], o[1]}; *(u32x2*)(dst + 8) = u32x2{o[2], o[3]}; *(u32x2*)(dst + 16) = u32x2{o[4], o[5]};
;     }
;   }
	v_mul_f32_e32 v2, s16, v56
	v_mul_f32_e32 v3, s16, v58
	v_mul_f32_e32 v4, s16, v60
	v_mul_f32_e32 v5, s16, v62
	v_mul_f32_e32 v6, s16, v64
	v_mul_f32_e32 v7, s16, v66
	v_mul_f32_e32 v8, s16, v68
	v_mul_f32_e32 v9, s16, v70
	v_mul_f32_e32 v10, s16, v72
	v_mul_f32_e32 v11, s16, v74
	v_mul_f32_e32 v12, s16, v76
	v_mul_f32_e32 v13, s16, v78
	v_mul_f32_e32 v14, s16, v80
	v_mul_f32_e32 v15, s16, v82
	v_mul_f32_e32 v16, s16, v84
	v_mul_f32_e32 v17, s16, v86
	v_mul_f32_e32 v18, s16, v57
	v_mul_f32_e32 v19, s16, v59
	v_mul_f32_e32 v20, s16, v61
	v_mul_f32_e32 v21, s16, v63
	v_mul_f32_e32 v22, s16, v65
	v_mul_f32_e32 v23, s16, v67
	v_mul_f32_e32 v24, s16, v69
	v_mul_f32_e32 v25, s16, v71
	v_mul_f32_e32 v26, s16, v73
	v_mul_f32_e32 v27, s16, v75
	v_mul_f32_e32 v28, s16, v77
	v_mul_f32_e32 v29, s16, v79
	v_mul_f32_e32 v30, s16, v81
	v_mul_f32_e32 v31, s16, v83
	v_mul_f32_e32 v32, s16, v85
	v_mul_f32_e32 v33, s16, v87
	s_nop 0
	v_cvt_scalef32_2xpk16_fp6_f32 v[40:45], v[2:17], v[18:33], 1.0
	global_load_dwordx4 v[56:59], v52, s[4:5] sc0 sc1 nt
	global_load_dwordx4 v[60:63], v52, s[4:5] offset:1024 sc0 sc1 nt
	global_load_dwordx4 v[64:67], v52, s[4:5] offset:2048 sc0 sc1 nt
	global_load_dwordx4 v[68:71], v52, s[4:5] offset:3072 sc0 sc1 nt
	global_load_dwordx4 v[72:75], v54, s[4:5] sc0 sc1 nt
	global_load_dwordx4 v[76:79], v54, s[4:5] offset:1024 sc0 sc1 nt
	global_load_dwordx4 v[80:83], v54, s[4:5] offset:2048 sc0 sc1 nt
	global_load_dwordx4 v[84:87], v54, s[4:5] offset:3072 sc0 sc1 nt
	s_add_u32 s2, s2, s12
	s_addc_u32 s3, s3, 0
	s_add_u32 s4, s4, s12
	s_addc_u32 s5, s5, 0
	s_waitcnt vmcnt(0)
	v_mul_f32_e32 v2, 4.0, v56
	v_mul_f32_e32 v3, 4.0, v58
	v_mul_f32_e32 v4, 4.0, v60
	v_mul_f32_e32 v5, 4.0, v62
	v_mul_f32_e32 v6, 4.0, v64
	v_mul_f32_e32 v7, 4.0, v66
	v_mul_f32_e32 v8, 4.0, v68
	v_mul_f32_e32 v9, 4.0, v70
	v_mul_f32_e32 v10, 4.0, v72
	v_mul_f32_e32 v11, 4.0, v74
	v_mul_f32_e32 v12, 4.0, v76
	v_mul_f32_e32 v13, 4.0, v78
	v_mul_f32_e32 v14, 4.0, v80
	v_mul_f32_e32 v15, 4.0, v82
	v_mul_f32_e32 v16, 4.0, v84
	v_mul_f32_e32 v17, 4.0, v86
	v_mul_f32_e32 v18, 4.0, v57
	v_mul_f32_e32 v19, 4.0, v59
	v_mul_f32_e32 v20, 4.0, v61
	v_mul_f32_e32 v21, 4.0, v63
	v_mul_f32_e32 v22, 4.0, v65
	v_mul_f32_e32 v23, 4.0, v67
	v_mul_f32_e32 v24, 4.0, v69
	v_mul_f32_e32 v25, 4.0, v71
	v_mul_f32_e32 v26, 4.0, v73
	v_mul_f32_e32 v27, 4.0, v75
	v_mul_f32_e32 v28, 4.0, v77
	v_mul_f32_e32 v29, 4.0, v79
	v_mul_f32_e32 v30, 4.0, v81
	v_mul_f32_e32 v31, 4.0, v83
	v_mul_f32_e32 v32, 4.0, v85
	v_mul_f32_e32 v33, 4.0, v87
	s_nop 0
	v_cvt_scalef32_2xpk16_fp6_f32 v[46:51], v[2:17], v[18:33], 1.0
	global_store_dwordx4 v53, v[40:43], s[6:7]
	global_store_dwordx4 v53, v[48:51], s[6:7] offset:1024
	global_store_dwordx4 v53, v[44:47], s[6:7] offset:2048
	s_add_u32 s6, s6, s13
	s_addc_u32 s7, s7, 0
	global_load_dwordx4 v[56:59], v52, s[2:3] sc0 sc1 nt
	global_load_dwordx4 v[60:63], v52, s[2:3] offset:1024 sc0 sc1 nt
	global_load_dwordx4 v[64:67], v52, s[2:3] offset:2048 sc0 sc1 nt
	global_load_dwordx4 v[68:71], v52, s[2:3] offset:3072 sc0 sc1 nt
	global_load_dwordx4 v[72:75], v54, s[2:3] sc0 sc1 nt
	global_load_dwordx4 v[76:79], v54, s[2:3] offset:1024 sc0 sc1 nt
	global_load_dwordx4 v[80:83], v54, s[2:3] offset:2048 sc0 sc1 nt
	global_load_dwordx4 v[84:87], v54, s[2:3] offset:3072 sc0 sc1 nt
	s_waitcnt vmcnt(0)
	v_mul_f32_e32 v2, s16, v56
	v_mul_f32_e32 v3, s16, v58
	v_mul_f32_e32 v4, s16, v60
	v_mul_f32_e32 v5, s16, v62
	v_mul_f32_e32 v6, s16, v64
	v_mul_f32_e32 v7, s16, v66
	v_mul_f32_e32 v8, s16, v68
	v_mul_f32_e32 v9, s16, v70
	v_mul_f32_e32 v10, s16, v72
	v_mul_f32_e32 v11, s16, v74
	v_mul_f32_e32 v12, s16, v76
	v_mul_f32_e32 v13, s16, v78
	v_mul_f32_e32 v14, s16, v80
	v_mul_f32_e32 v15, s16, v82
	v_mul_f32_e32 v16, s16, v84
	v_mul_f32_e32 v17, s16, v86
	v_mul_f32_e32 v18, s16, v57
	v_mul_f32_e32 v19, s16, v59
	v_mul_f32_e32 v20, s16, v61
	v_mul_f32_e32 v21, s16, v63
	v_mul_f32_e32 v22, s16, v65
	v_mul_f32_e32 v23, s16, v67
	v_mul_f32_e32 v24, s16, v69
	v_mul_f32_e32 v25, s16, v71
	v_mul_f32_e32 v26, s16, v73
	v_mul_f32_e32 v27, s16, v75
	v_mul_f32_e32 v28, s16, v77
	v_mul_f32_e32 v29, s16, v79
	v_mul_f32_e32 v30, s16, v81
	v_mul_f32_e32 v31, s16, v83
	v_mul_f32_e32 v32, s16, v85
	v_mul_f32_e32 v33, s16, v87
	s_nop 0
	v_cvt_scalef32_2xpk16_fp6_f32 v[40:45], v[2:17], v[18:33], 1.0
	global_load_dwordx4 v[56:59], v52, s[4:5] sc0 sc1 nt
	global_load_dwordx4 v[60:63], v52, s[4:5] offset:1024 sc0 sc1 nt
	global_load_dwordx4 v[64:67], v52, s[4:5] offset:2048 sc0 sc1 nt
	global_load_dwordx4 v[68:71], v52, s[4:5] offset:3072 sc0 sc1 nt
	global_load_dwordx4 v[72:75], v54, s[4:5] sc0 sc1 nt
	global_load_dwordx4 v[76:79], v54, s[4:5] offset:1024 sc0 sc1 nt
	global_load_dwordx4 v[80:83], v54, s[4:5] offset:2048 sc0 sc1 nt
	global_load_dwordx4 v[84:87], v54, s[4:5] offset:3072 sc0 sc1 nt
	s_add_u32 s2, s2, s12
	s_addc_u32 s3, s3, 0
	s_add_u32 s4, s4, s12
	s_addc_u32 s5, s5, 0
	s_waitcnt vmcnt(0)
; __global__ void __launch_bounds__(256, 2) fwd_megakernel(Params p) {
;     ...
;   if (bid >= (nb >> 1)) {
;   for (size_t blk = (size_t)bid * 256 + tid; blk < (size_t)16384 * 64; blk += (size_t)nb * 256) {
; #pragma unroll
;     for (int tb = 0; tb < 2; ++tb) {
;       const float* src = (tb ? p.peer_up : p.peer_down) + blk * 32;
;       const float sc = tb ? UP_SCALE : DOWN_SCALE;
;       v16f va, vb;
; #pragma unroll
;       for (int q = 0; q < 4; ++q) {
;         const float4 x = *(const float4*)(src + q * 8), y = *(const float4*)(src + q * 8 + 4);
;         va[q * 4] = x.x * sc; vb[q * 4] = x.y * sc; va[q * 4 + 1] = x.z * sc; vb[q * 4 + 1] = x.w * sc;
;         va[q * 4 + 2] = y.x * sc; vb[q * 4 + 2] = y.y * sc; va[q * 4 + 3] = y.z * sc; vb[q * 4 + 3] = y.w * sc;
;       }
;       const v6u o = __builtin_amdgcn_cvt_scalef32_2xpk16_fp6_f32(va, vb, 1.0f);
;       unsigned char* dst = (tb ? p.up8 : p.down8) + blk * 24;
;       *(u32x2*)dst = u32x2{o[0], o[1]}; *(u32x2*)(dst + 8) = u32x2{o[2], o[3]}; *(u32x2*)(dst + 16) = u32x2{o[4], o[5]};
;     }
;   }
	v_mul_f32_e32 v2, 4.0, v56
	v_mul_f32_e32 v3, 4.0, v58
	v_mul_f32_e32 v4, 4.0, v60
	v_mul_f32_e32 v5, 4.0, v62
	v_mul_f32_e32 v6, 4.0, v64
	v_mul_f32_e32 v7, 4.0, v66
	v_mul_f32_e32 v8, 4.0, v68
	v_mul_f32_e32 v9, 4.0, v70
	v_mul_f32_e32 v10, 4.0, v72
	v_mul_f32_e32 v11, 4.0, v74
	v_mul_f32_e32 v12, 4.0, v76
	v_mul_f32_e32 v13, 4.0, v78
	v_mul_f32_e32 v14, 4.0, v80
	v_mul_f32_e32 v15, 4.0, v82
	v_mul_f32_e32 v16, 4.0, v84
	v_mul_f32_e32 v17, 4.0, v86
	v_mul_f32_e32 v18, 4.0, v57
	v_mul_f32_e32 v19, 4.0, v59
	v_mul_f32_e32 v20, 4.0, v61
	v_mul_f32_e32 v21, 4.0, v63
	v_mul_f32_e32 v22, 4.0, v65
	v_mul_f32_e32 v23, 4.0, v67
	v_mul_f32_e32 v24, 4.0, v69
	v_mul_f32_e32 v25, 4.0, v71
	v_mul_f32_e32 v26, 4.0, v73
	v_mul_f32_e32 v27, 4.0, v75
	v_mul_f32_e32 v28, 4.0, v77
	v_mul_f32_e32 v29, 4.0, v79
	v_mul_f32_e32 v30, 4.0, v81
	v_mul_f32_e32 v31, 4.0, v83
	v_mul_f32_e32 v32, 4.0, v85
	v_mul_f32_e32 v33, 4.0, v87
	s_nop 0
	v_cvt_scalef32_2xpk16_fp6_f32 v[46:51], v[2:17], v[18:33], 1.0
	global_store_dwordx4 v53, v[40:43], s[6:7]
	global_store_dwordx4 v53, v[48:51], s[6:7] offset:1024
	global_store_dwordx4 v53, v[44:47], s[6:7] offset:2048
	s_add_u32 s6, s6, s13
	s_addc_u32 s7, s7, 0
	global_load_dwordx4 v[56:59], v52, s[2:3] sc0 sc1 nt
	global_load_dwordx4 v[60:63], v52, s[2:3] offset:1024 sc0 sc1 nt
	global_load_dwordx4 v[64:67], v52, s[2:3] offset:2048 sc0 sc1 nt
	global_load_dwordx4 v[68:71], v52, s[2:3] offset:3072 sc0 sc1 nt
	global_load_dwordx4 v[72:75], v54, s[2:3] sc0 sc1 nt
	global_load_dwordx4 v[76:79], v54, s[2:3] offset:1024 sc0 sc1 nt
	global_load_dwordx4 v[80:83], v54, s[2:3] offset:2048 sc0 sc1 nt
	global_load_dwordx4 v[84:87], v54, s[2:3] offset:3072 sc0 sc1 nt
	s_waitcnt vmcnt(0)
	v_mul_f32_e32 v2, s16, v56
	v_mul_f32_e32 v3, s16, v58
	v_mul_f32_e32 v4, s16, v60
	v_mul_f32_e32 v5, s16, v62
	v_mul_f32_e32 v6, s16, v64
	v_mul_f32_e32 v7, s16, v66
	v_mul_f32_e32 v8, s16, v68
	v_mul_f32_e32 v9, s16, v70
	v_mul_f32_e32 v10, s16, v72
	v_mul_f32_e32 v11, s16, v74
	v_mul_f32_e32 v12, s16, v76
	v_mul_f32_e32 v13, s16, v78
	v_mul_f32_e32 v14, s16, v80
	v_mul_f32_e32 v15, s16, v82
	v_mul_f32_e32 v16, s16, v84
	v_mul_f32_e32 v17, s16, v86
	v_mul_f32_e32 v18, s16, v57
	v_mul_f32_e32 v19, s16, v59
	v_mul_f32_e32 v20, s16, v61
	v_mul_f32_e32 v21, s16, v63
	v_mul_f32_e32 v22, s16, v65
	v_mul_f32_e32 v23, s16, v67
	v_mul_f32_e32 v24, s16, v69
	v_mul_f32_e32 v25, s16, v71
	v_mul_f32_e32 v26, s16, v73
	v_mul_f32_e32 v27, s16, v75
	v_mul_f32_e32 v28, s16, v77
	v_mul_f32_e32 v29, s16, v79
	v_mul_f32_e32 v30, s16, v81
	v_mul_f32_e32 v31, s16, v83
	v_mul_f32_e32 v32, s16, v85
	v_mul_f32_e32 v33, s16, v87
	s_nop 0
	v_cvt_scalef32_2xpk16_fp6_f32 v[40:45], v[2:17], v[18:33], 1.0
	global_load_dwordx4 v[56:59], v52, s[4:5] sc0 sc1 nt
	global_load_dwordx4 v[60:63], v52, s[4:5] offset:1024 sc0 sc1 nt
	global_load_dwordx4 v[64:67], v52, s[4:5] offset:2048 sc0 sc1 nt
	global_load_dwordx4 v[68:71], v52, s[4:5] offset:3072 sc0 sc1 nt
	global_load_dwordx4 v[72:75], v54, s[4:5] sc0 sc1 nt
	global_load_dwordx4 v[76:79], v54, s[4:5] offset:1024 sc0 sc1 nt
	global_load_dwordx4 v[80:83], v54, s[4:5] offset:2048 sc0 sc1 nt
	global_load_dwordx4 v[84:87], v54, s[4:5] offset:3072 sc0 sc1 nt
	s_waitcnt vmcnt(0)
	v_mul_f32_e32 v2, 4.0, v56
	v_mul_f32_e32 v3, 4.0, v58
	v_mul_f32_e32 v4, 4.0, v60
	v_mul_f32_e32 v5, 4.0, v62
	v_mul_f32_e32 v6, 4.0, v64
	v_mul_f32_e32 v7, 4.0, v66
	v_mul_f32_e32 v8, 4.0, v68
	v_mul_f32_e32 v9, 4.0, v70
	v_mul_f32_e32 v10, 4.0, v72
	v_mul_f32_e32 v11, 4.0, v74
	v_mul_f32_e32 v12, 4.0, v76
	v_mul_f32_e32 v13, 4.0, v78
	v_mul_f32_e32 v14, 4.0, v80
	v_mul_f32_e32 v15, 4.0, v82
	v_mul_f32_e32 v16, 4.0, v84
	v_mul_f32_e32 v17, 4.0, v86
	v_mul_f32_e32 v18, 4.0, v57
	v_mul_f32_e32 v19, 4.0, v59
	v_mul_f32_e32 v20, 4.0, v61
	v_mul_f32_e32 v21, 4.0, v63
	v_mul_f32_e32 v22, 4.0, v65
	v_mul_f32_e32 v23, 4.0, v67
	v_mul_f32_e32 v24, 4.0, v69
	v_mul_f32_e32 v25, 4.0, v71
	v_mul_f32_e32 v26, 4.0, v73
	v_mul_f32_e32 v27, 4.0, v75
	v_mul_f32_e32 v28, 4.0, v77
	v_mul_f32_e32 v29, 4.0, v79
	v_mul_f32_e32 v30, 4.0, v81
	v_mul_f32_e32 v31, 4.0, v83
	v_mul_f32_e32 v32, 4.0, v85
	v_mul_f32_e32 v33, 4.0, v87
	s_nop 0
	v_cvt_scalef32_2xpk16_fp6_f32 v[46:51], v[2:17], v[18:33], 1.0
	global_store_dwordx4 v53, v[40:43], s[6:7]
	global_store_dwordx4 v53, v[48:51], s[6:7] offset:1024
	global_store_dwordx4 v53, v[44:47], s[6:7] offset:2048
	s_add_u32 s6, s6, s13
	s_addc_u32 s7, s7, 0
	s_branch .Lenc_end_b

; DEV unsigned xb_ld(unsigned* p) { return __hip_atomic_load(p, __ATOMIC_RELAXED, __HIP_MEMORY_SCOPE_AGENT); }
; DEV unsigned xb_add(unsigned* p, unsigned v) { return __hip_atomic_fetch_add(p, v, __ATOMIC_RELAXED, __HIP_MEMORY_SCOPE_AGENT); }
; #define XB_SPIN(cond, bar) do { unsigned _sp = 0; while (cond) { \
;     if ((++_sp & 255u) == 0u) { if (xb_ld(&(bar)[XB_TMO])) break; if (_sp > XB_SPIN_CAP) { atomicAdd(&(bar)[XB_TMO], 1u); break; } } } } while (0)
; DEV void xcd_barrier(unsigned* bar, unsigned x, volatile unsigned* st) {
;   asm volatile("s_waitcnt vmcnt(0)" ::: "memory");
;   __syncthreads();
;   if (threadIdx.x == 0) {
;     __builtin_amdgcn_s_waitcnt(0);
;     unsigned nloc = st[0], nx = st[1];
;     if (nloc == 0u) { xcd_barrier_complete(bar, x, nloc, nx); st[0] = nloc; st[1] = nx; }
;     const unsigned old = xb_add(&bar[XB_XSUB(x)], 1u);
;     const unsigned gen = old / nloc;
;     if (old + 1u == (gen + 1u) * nloc) {
;       __builtin_amdgcn_fence(__ATOMIC_RELEASE, "agent");
;       asm volatile("s_waitcnt vmcnt(0)" ::: "memory");
;       const unsigned og = xb_add(&bar[XB_TOP], 1u);
;       const unsigned tg = og / nx;
;       if (og + 1u == (tg + 1u) * nx) xb_add(&bar[XB_TOPGEN], 1u);
;       else XB_SPIN(xb_ld(&bar[XB_TOPGEN]) == tg, bar);
.Lenc_end_b:
.LBB0_1384:
	s_waitcnt vmcnt(0)
	s_barrier
	s_mov_b64 s[0:1], exec
	v_readlane_b32 s2, v254, 2
	v_readlane_b32 s3, v254, 3
	s_and_b64 s[2:3], s[0:1], s[2:3]
	s_mov_b64 exec, s[2:3]
	s_cbranch_execz .LBB0_1436
	s_mov_b64 s[2:3], src_shared_base
	v_mov_b32_e32 v2, 0x12100
	v_mov_b32_e32 v3, s3
	s_waitcnt vmcnt(0) expcnt(0) lgkmcnt(0)
	flat_load_dword v4, v[2:3] sc0 sc1
	s_waitcnt vmcnt(0)
	v_mov_b32_e32 v2, 0x12104
	flat_load_dword v2, v[2:3] sc0 sc1
	s_waitcnt vmcnt(0) lgkmcnt(0)
	v_cmp_eq_u32_e32 vcc, 0, v4
	s_and_saveexec_b64 s[6:7], vcc
	s_cbranch_execz .LBB0_1400
	s_add_u32 s8, s70, 0x1000
	s_addc_u32 s9, s71, 0
	s_add_u32 s10, s70, 0x1100
	s_addc_u32 s11, s71, 0
	s_add_u32 s12, s70, 0x1200
	s_addc_u32 s13, s71, 0
	s_add_u32 s16, s70, 0x1300
	s_addc_u32 s17, s71, 0
	s_mov_b32 s2, 1
	v_mov_b32_e32 v17, 0
	s_branch .LBB0_1388

; DEV void peer_route_item(const Params& p, int item, char* smem) {
;   int tid_ = threadIdx.x;
;   asm volatile("" : "+v"(tid_));
;   const int tid = tid_, lane = tid & 63, w = tid >> 6, lq = lane & 15, g4 = lane >> 4;
;   const int hh = item >> 8, tt = item & 255;
;   const int tokL = w * 16 + lq, tok = tt * 64 + tokL;
;   u16* Ks = (u16*)smem;
;   float* topv = (float*)(smem + 34816);
;   int* topi = (int*)(smem + 34816 + 8192);
;   float* cvs = (float*)(smem + 34816 + 16384);
;   int* candA = (int*)(smem + 34816 + 16384 + 13056);
;   int* candB = candA + 50;
;   const float NEG_INF = -__builtin_inff();
; __global__ void __launch_bounds__(256, 2) fwd_megakernel(Params p) {
;     ...
;   for (int it = bid; it < 8 * 256; it += nb) peer_route_item(p, it, smem);
;   if (bid >= (nb >> 1)) {
.LBB0_1436:
	s_or_b64 exec, exec, s[0:1]
	s_ashr_i32 s0, s92, 1
	v_mov_b32_e32 v34, v0
	s_cmp_ge_i32 s94, s0
	s_waitcnt lgkmcnt(0)
	s_barrier
	s_cselect_b64 s[72:73], -1, 0
	s_cmp_lt_i32 s94, s0
	v_ashrrev_i32_e32 v35, 31, v34
	s_cbranch_scc0 .LBB0_1441
.LBB0_1441:
	v_readlane_b32 s0, v255, 43
	v_readlane_b32 s1, v255, 44
	s_andn2_b64 vcc, exec, s[0:1]
	s_cbranch_vccnz .LBB0_1510
	v_mbcnt_lo_u32_b32 v1, -1, 0
	v_mbcnt_hi_u32_b32 v32, -1, v1
	v_and_b32_e32 v1, 64, v32
	s_movk_i32 s2, 0x110
	v_mov_b32_e32 v3, 0
	s_movk_i32 s3, 0xf800
	s_mov_b32 s75, 0
	s_movk_i32 s4, 0xff80
	s_movk_i32 s5, 0x7f
	s_movk_i32 s33, 0xcc
	s_movk_i32 s58, 0xffc0
	v_xor_b32_e32 v33, 16, v32
	v_add_u32_e32 v36, 64, v1
	v_xor_b32_e32 v37, 32, v32
	v_bfrev_b32_e32 v38, 1
	s_mov_b32 s59, s94
	s_branch .LBB0_1444

; __global__ void __launch_bounds__(256, 2) fwd_megakernel(Params p) {
;     ...
;   if (bid >= (nb >> 1)) {
;   for (size_t blk = (size_t)bid * 256 + tid; blk < (size_t)16384 * 64; blk += (size_t)nb * 256) {
; #pragma unroll
;     for (int tb = 0; tb < 2; ++tb) {
;       const float* src = (tb ? p.peer_up : p.peer_down) + blk * 32;
;       const float sc = tb ? UP_SCALE : DOWN_SCALE;
;       v16f va, vb;
; #pragma unroll
;       for (int q = 0; q < 4; ++q) {
;         const float4 x = *(const float4*)(src + q * 8), y = *(const float4*)(src + q * 8 + 4);
;         va[q * 4] = x.x * sc; vb[q * 4] = x.y * sc; va[q * 4 + 1] = x.z * sc; vb[q * 4 + 1] = x.w * sc;
;         va[q * 4 + 2] = y.x * sc; vb[q * 4 + 2] = y.y * sc; va[q * 4 + 3] = y.z * sc; vb[q * 4 + 3] = y.w * sc;
;       }
;       const v6u o = __builtin_amdgcn_cvt_scalef32_2xpk16_fp6_f32(va, vb, 1.0f);
;       unsigned char* dst = (tb ? p.up8 : p.down8) + blk * 24;
;       *(u32x2*)dst = u32x2{o[0], o[1]}; *(u32x2*)(dst + 8) = u32x2{o[2], o[3]}; *(u32x2*)(dst + 16) = u32x2{o[4], o[5]};
;     }
;   }
;   }
;   }
;   xcd_barrier(p.bar, xcc, xb_st);
.LBB0_1510:
	s_and_b64 vcc, exec, s[72:73]
	s_cbranch_vccz .LBB0_1515
.LBB0_1515:
	s_waitcnt vmcnt(0)
	s_barrier
	s_mov_b64 s[0:1], exec
	v_readlane_b32 s2, v254, 2
	v_readlane_b32 s3, v254, 3
	s_and_b64 s[2:3], s[0:1], s[2:3]
	s_mov_b64 exec, s[2:3]
	s_cbranch_execz .LBB0_1567
	s_mov_b64 s[2:3], src_shared_base
	v_mov_b32_e32 v2, 0x12100
	v_mov_b32_e32 v3, s3
	s_waitcnt vmcnt(0) expcnt(0) lgkmcnt(0)
	flat_load_dword v4, v[2:3] sc0 sc1
	s_waitcnt vmcnt(0)
	v_mov_b32_e32 v2, 0x12104
	flat_load_dword v2, v[2:3] sc0 sc1
	s_waitcnt vmcnt(0) lgkmcnt(0)
	v_cmp_eq_u32_e32 vcc, 0, v4
	s_and_saveexec_b64 s[2:3], vcc
	s_cbranch_execz .LBB0_1531
	s_add_u32 s4, s70, 0x1000
	s_addc_u32 s5, s71, 0
	s_add_u32 s6, s70, 0x1100
	s_addc_u32 s7, s71, 0
	s_add_u32 s8, s70, 0x1200
	s_addc_u32 s9, s71, 0
	s_add_u32 s10, s70, 0x1300
	s_addc_u32 s11, s71, 0
	s_mov_b32 s18, 1
	v_mov_b32_e32 v17, 0
	s_branch .LBB0_1519
